# UP epilogue: sigmoid denominators formed with packed adds (bitwise identical results)
# speedup vs baseline: 1.0109x; 1.0109x over previous
; #define PG8_STAGE(bufoff, gbase, voff) do { _Pragma("unroll") for (int _i = 0; _i < 2; ++_i) \
;         __builtin_amdgcn_global_load_lds((const unsigned*)((const char*)(gbase) + (voff)[_i]), (LAS unsigned*)(lds + (bufoff) + ldsw + _i * 8192), 16, 0, 0); } while (0)
; #define PG8_LDA(dst, b, h) do { _Pragma("unroll") for (int m = 0; m < 4; ++m) _Pragma("unroll") for (int k = 0; k < 2; ++k) dst[m][k] = *(const LAS bf16x8*)(lds + PG8_SA(b, h) + aoff + m * 2048 + k * 1024); } while (0)
; #define PG8_LDB(dst, b, h) do { _Pragma("unroll") for (int n = 0; n < 2; ++n) _Pragma("unroll") for (int k = 0; k < 2; ++k) dst[n][k] = *(const LAS bf16x8*)(lds + PG8_SB(b, h) + boff + n * 2048 + k * 1024); } while (0)
; #define PG8_MMA(ai, bj, At, Bt) do { __builtin_amdgcn_s_setprio(1); _Pragma("unroll") for (int m = 0; m < 4; ++m) _Pragma("unroll") for (int n = 0; n < 2; ++n) _Pragma("unroll") for (int k = 0; k < 2; ++k) \
;         acc[ai][bj][m][n] = __builtin_amdgcn_mfma_f32_16x16x32_bf16(Bt[n][k], At[m][k], acc[ai][bj][m][n], 0, 0, 0); __builtin_amdgcn_s_setprio(0); } while (0)
; #define PG8_WAIT_V(n) asm volatile("s_waitcnt vmcnt(" #n ")" ::: "memory")
; #define PG8_WAIT_L(n) asm volatile("s_waitcnt lgkmcnt(" #n ")" ::: "memory")
; template <class Epi>
; __device__ __forceinline__ void gemm_phase(int wv, LAS unsigned char* lds, const Gemm g, const StaticOrder& S, const Epi& E) {
;     ...
;         for (int t = 0; t < nt; t += 2) {
;             const bool last = (t == nt - 2);
;             const char* a1 = cA + (size_t)(t + 1) * kstep;
;             const char* a2 = last ? nA : cA + (size_t)(t + 2) * kstep; const char* b2 = last ? nB : cB + (size_t)(t + 2) * kstep;
;             const char* a3 = a2 + kstep; const char* b3 = b2 + kstep;
;             PG8_LDB(B0, 0, 0); PG8_SCHED; PG8_LDA(At, 0, 0); PG8_STAGE(PG8_SA(1, 1), a1 + hstepA, voffA);
;             PG8_WAIT_L(8); PG8_BAR; PG8_WAIT_L(0); PG8_MMA(0, 0, At, B0); PG8_BAR; PG8_SCHED;
;             PG8_LDB(B1, 0, 1); PG8_STAGE(PG8_SB(0, 0), b2, voffB);
;             PG8_BAR; PG8_WAIT_L(0); PG8_MMA(0, 1, At, B1); PG8_BAR;
;             PG8_LDA(At, 0, 1); PG8_STAGE(PG8_SA(0, 0), a2, voffA);
;             PG8_BAR; PG8_WAIT_L(0); PG8_MMA(1, 0, At, B0); PG8_BAR; PG8_SCHED;
;             PG8_STAGE(PG8_SB(0, 1), b2 + hstepB, voffB);
;             PG8_WAIT_V(6); PG8_BAR; PG8_MMA(1, 1, At, B1); PG8_BAR;
.LBB0_455:
	s_add_u32 s6, s4, 0xfffc0080
	s_addc_u32 s7, s5, -1
	s_add_i32 s42, 0, 0x10000
	v_add_u32_e32 v110, s42, v1
	ds_read_b128 v[98:101], v110
	ds_read_b128 v[102:105], v110 offset:1024
	ds_read_b128 v[106:109], v110 offset:2048
	ds_read_b128 v[110:113], v110 offset:3072
	s_cmp_eq_u32 s17, 12
	s_cselect_b32 s9, s10, s7
	s_cselect_b32 s8, s11, s6
	s_cselect_b32 s7, s13, s16
	s_cselect_b32 s6, s14, s15
	v_lshl_add_u64 v[192:193], s[4:5], 0, v[180:181]
	s_add_i32 m0, s60, 0xc000
	ds_read_b128 v[114:117], v179
	ds_read_b128 v[118:121], v179 offset:1024
	ds_read_b128 v[122:125], v179 offset:2048
	ds_read_b128 v[126:129], v179 offset:3072
	ds_read_b128 v[138:141], v179 offset:4096
	ds_read_b128 v[162:165], v179 offset:5120
	ds_read_b128 v[184:187], v179 offset:6144
	ds_read_b128 v[188:191], v179 offset:7168
	global_load_lds_dwordx4 v[192:193], off
	v_lshl_add_u64 v[192:193], s[4:5], 0, v[182:183]
	s_add_i32 m0, s60, 0xe000
	s_nop 0
	global_load_lds_dwordx4 v[192:193], off
	s_waitcnt lgkmcnt(8)
	s_barrier
	s_waitcnt lgkmcnt(0)
	s_setprio 1
	s_waitcnt lgkmcnt(0)
	v_mfma_f32_16x16x32_bf16 v[146:149], v[98:101], v[114:117], v[146:149]
	v_mfma_f32_16x16x32_bf16 v[46:49], v[106:109], v[114:117], v[46:49]
	v_mfma_f32_16x16x32_bf16 v[134:137], v[98:101], v[122:125], v[134:137]
	v_mfma_f32_16x16x32_bf16 v[38:41], v[106:109], v[122:125], v[38:41]
	v_mfma_f32_16x16x32_bf16 v[130:133], v[98:101], v[138:141], v[130:133]
	v_mfma_f32_16x16x32_bf16 v[34:37], v[106:109], v[138:141], v[34:37]
	v_mfma_f32_16x16x32_bf16 v[142:145], v[98:101], v[184:187], v[142:145]
	v_mfma_f32_16x16x32_bf16 v[42:45], v[106:109], v[184:187], v[42:45]
	v_mfma_f32_16x16x32_bf16 v[146:149], v[102:105], v[118:121], v[146:149]
	v_mfma_f32_16x16x32_bf16 v[46:49], v[110:113], v[118:121], v[46:49]
	v_mfma_f32_16x16x32_bf16 v[134:137], v[102:105], v[126:129], v[134:137]
	v_mfma_f32_16x16x32_bf16 v[38:41], v[110:113], v[126:129], v[38:41]
	v_mfma_f32_16x16x32_bf16 v[130:133], v[102:105], v[162:165], v[130:133]
	v_mfma_f32_16x16x32_bf16 v[34:37], v[110:113], v[162:165], v[34:37]
	v_mfma_f32_16x16x32_bf16 v[142:145], v[102:105], v[188:191], v[142:145]
	v_mfma_f32_16x16x32_bf16 v[42:45], v[110:113], v[188:191], v[42:45]
	s_setprio 0
	s_barrier
	s_add_i32 s44, 0, 0x14000
	s_add_i32 s42, s42, s59
	v_add_u32_e32 v204, s44, v1
	v_lshl_add_u64 v[212:213], s[6:7], 0, v[174:175]
	s_mov_b32 m0, s42
	ds_read_b128 v[192:195], v204
	ds_read_b128 v[196:199], v204 offset:1024
	ds_read_b128 v[200:203], v204 offset:2048
	ds_read_b128 v[204:207], v204 offset:3072
	global_load_lds_dwordx4 v[212:213], off
	v_lshl_add_u64 v[214:215], s[6:7], 0, v[170:171]
	s_add_i32 m0, s42, 0x2000
	s_nop 0
	global_load_lds_dwordx4 v[214:215], off
	s_barrier
	s_waitcnt lgkmcnt(0)
	s_setprio 1
	s_waitcnt lgkmcnt(0)
	v_mfma_f32_16x16x32_bf16 v[166:169], v[192:195], v[114:117], v[166:169]
	v_mfma_f32_16x16x32_bf16 v[62:65], v[200:203], v[114:117], v[62:65]
	v_mfma_f32_16x16x32_bf16 v[54:57], v[200:203], v[122:125], v[54:57]
	v_mfma_f32_16x16x32_bf16 v[50:53], v[200:203], v[138:141], v[50:53]
	v_mfma_f32_16x16x32_bf16 v[58:61], v[200:203], v[184:187], v[58:61]
	v_mfma_f32_16x16x32_bf16 v[166:169], v[196:199], v[118:121], v[166:169]
	v_mfma_f32_16x16x32_bf16 v[62:65], v[204:207], v[118:121], v[62:65]
	v_mfma_f32_16x16x32_bf16 v[114:117], v[192:195], v[122:125], v[154:157]
	v_mfma_f32_16x16x32_bf16 v[54:57], v[204:207], v[126:129], v[54:57]
	v_mfma_f32_16x16x32_bf16 v[118:121], v[192:195], v[138:141], v[150:153]
	v_mfma_f32_16x16x32_bf16 v[50:53], v[204:207], v[162:165], v[50:53]
	v_mfma_f32_16x16x32_bf16 v[122:125], v[192:195], v[184:187], v[158:161]
	v_mfma_f32_16x16x32_bf16 v[58:61], v[204:207], v[188:191], v[58:61]
	v_mfma_f32_16x16x32_bf16 v[114:117], v[196:199], v[126:129], v[114:117]
	v_mfma_f32_16x16x32_bf16 v[118:121], v[196:199], v[162:165], v[118:121]
	v_mfma_f32_16x16x32_bf16 v[122:125], v[196:199], v[188:191], v[122:125]
	s_setprio 0
	s_mov_b32 m0, s60
	v_lshl_add_u64 v[216:217], s[8:9], 0, v[176:177]
	s_barrier
	ds_read_b128 v[126:129], v179 offset:16384
	ds_read_b128 v[138:141], v179 offset:17408
	ds_read_b128 v[150:153], v179 offset:18432
	ds_read_b128 v[154:157], v179 offset:19456
	ds_read_b128 v[158:161], v179 offset:20480
	ds_read_b128 v[162:165], v179 offset:21504
	ds_read_b128 v[184:187], v179 offset:22528
	ds_read_b128 v[188:191], v179 offset:23552
	global_load_lds_dwordx4 v[216:217], off
	v_lshl_add_u64 v[218:219], s[8:9], 0, v[172:173]
	s_mov_b32 m0, s61
	s_nop 0
	global_load_lds_dwordx4 v[218:219], off
	s_barrier
	s_waitcnt lgkmcnt(0)
	s_setprio 1
	s_waitcnt lgkmcnt(0)
	v_mfma_f32_16x16x32_bf16 v[78:81], v[98:101], v[126:129], v[78:81]
	v_mfma_f32_16x16x32_bf16 v[14:17], v[106:109], v[126:129], v[14:17]
	v_mfma_f32_16x16x32_bf16 v[70:73], v[98:101], v[150:153], v[70:73]
	v_mfma_f32_16x16x32_bf16 v[6:9], v[106:109], v[150:153], v[6:9]
	v_mfma_f32_16x16x32_bf16 v[66:69], v[98:101], v[158:161], v[66:69]
	v_mfma_f32_16x16x32_bf16 v[2:5], v[106:109], v[158:161], v[2:5]
	v_mfma_f32_16x16x32_bf16 v[74:77], v[98:101], v[184:187], v[74:77]
	v_mfma_f32_16x16x32_bf16 v[10:13], v[106:109], v[184:187], v[10:13]
	v_mfma_f32_16x16x32_bf16 v[78:81], v[102:105], v[138:141], v[78:81]
	v_mfma_f32_16x16x32_bf16 v[14:17], v[110:113], v[138:141], v[14:17]
	v_mfma_f32_16x16x32_bf16 v[70:73], v[102:105], v[154:157], v[70:73]
	v_mfma_f32_16x16x32_bf16 v[6:9], v[110:113], v[154:157], v[6:9]
	v_mfma_f32_16x16x32_bf16 v[66:69], v[102:105], v[162:165], v[66:69]
	v_mfma_f32_16x16x32_bf16 v[2:5], v[110:113], v[162:165], v[2:5]
	v_mfma_f32_16x16x32_bf16 v[74:77], v[102:105], v[188:191], v[74:77]
	v_mfma_f32_16x16x32_bf16 v[10:13], v[110:113], v[188:191], v[10:13]
	s_setprio 0
	s_barrier
; #define PG8_STAGE(bufoff, gbase, voff) do { _Pragma("unroll") for (int _i = 0; _i < 2; ++_i) \
;         __builtin_amdgcn_global_load_lds((const unsigned*)((const char*)(gbase) + (voff)[_i]), (LAS unsigned*)(lds + (bufoff) + ldsw + _i * 8192), 16, 0, 0); } while (0)
; #define PG8_LDA(dst, b, h) do { _Pragma("unroll") for (int m = 0; m < 4; ++m) _Pragma("unroll") for (int k = 0; k < 2; ++k) dst[m][k] = *(const LAS bf16x8*)(lds + PG8_SA(b, h) + aoff + m * 2048 + k * 1024); } while (0)
; #define PG8_LDB(dst, b, h) do { _Pragma("unroll") for (int n = 0; n < 2; ++n) _Pragma("unroll") for (int k = 0; k < 2; ++k) dst[n][k] = *(const LAS bf16x8*)(lds + PG8_SB(b, h) + boff + n * 2048 + k * 1024); } while (0)
; #define PG8_MMA(ai, bj, At, Bt) do { __builtin_amdgcn_s_setprio(1); _Pragma("unroll") for (int m = 0; m < 4; ++m) _Pragma("unroll") for (int n = 0; n < 2; ++n) _Pragma("unroll") for (int k = 0; k < 2; ++k) \
;         acc[ai][bj][m][n] = __builtin_amdgcn_mfma_f32_16x16x32_bf16(Bt[n][k], At[m][k], acc[ai][bj][m][n], 0, 0, 0); __builtin_amdgcn_s_setprio(0); } while (0)
; #define PG8_WAIT_V(n) asm volatile("s_waitcnt vmcnt(" #n ")" ::: "memory")
; #define PG8_WAIT_L(n) asm volatile("s_waitcnt lgkmcnt(" #n ")" ::: "memory")
; #define PG8_BAR __builtin_amdgcn_s_barrier()
; #define PG8_SCHED __builtin_amdgcn_sched_barrier(0)
; template <class Epi>
; __device__ __forceinline__ void gemm_phase(int wv, LAS unsigned char* lds, const Gemm g, const StaticOrder& S, const Epi& E) {
;     ...
;             PG8_WAIT_V(6); PG8_BAR; PG8_MMA(1, 1, At, B1); PG8_BAR;
;             PG8_LDB(B0, 1, 0); PG8_SCHED; PG8_LDA(At, 1, 0); PG8_STAGE(PG8_SA(0, 1), a2 + hstepA, voffA);
;             PG8_WAIT_L(8); PG8_BAR; PG8_WAIT_L(0); PG8_MMA(0, 0, At, B0); PG8_BAR; PG8_SCHED;
;             PG8_LDB(B1, 1, 1); PG8_STAGE(PG8_SB(1, 0), b3, voffB);
;             PG8_BAR; PG8_WAIT_L(0); PG8_MMA(0, 1, At, B1); PG8_BAR;
;             PG8_LDA(At, 1, 1); PG8_STAGE(PG8_SA(1, 0), a3, voffA);
;             PG8_BAR; PG8_WAIT_L(0); PG8_MMA(1, 0, At, B0); PG8_BAR; PG8_SCHED;
	s_add_u32 s54, s6, 0x40000
	s_addc_u32 s55, s7, 0
	s_add_i32 s42, s44, s59
	v_lshl_add_u64 v[98:99], s[54:55], 0, v[174:175]
	s_mov_b32 m0, s42
	s_nop 0
	global_load_lds_dwordx4 v[98:99], off
	v_lshl_add_u64 v[98:99], s[54:55], 0, v[170:171]
	s_add_i32 m0, s42, 0x2000
	s_nop 0
	global_load_lds_dwordx4 v[98:99], off
	s_waitcnt vmcnt(6)
	s_barrier
	s_setprio 1
	v_mfma_f32_16x16x32_bf16 v[94:97], v[192:195], v[126:129], v[94:97]
	v_mfma_f32_16x16x32_bf16 v[30:33], v[200:203], v[126:129], v[30:33]
	v_mfma_f32_16x16x32_bf16 v[86:89], v[192:195], v[150:153], v[86:89]
	v_mfma_f32_16x16x32_bf16 v[26:29], v[200:203], v[150:153], v[26:29]
	v_mfma_f32_16x16x32_bf16 v[82:85], v[192:195], v[158:161], v[82:85]
	v_mfma_f32_16x16x32_bf16 v[18:21], v[200:203], v[158:161], v[18:21]
	v_mfma_f32_16x16x32_bf16 v[90:93], v[192:195], v[184:187], v[90:93]
	v_mfma_f32_16x16x32_bf16 v[22:25], v[200:203], v[184:187], v[22:25]
	v_mfma_f32_16x16x32_bf16 v[94:97], v[196:199], v[138:141], v[94:97]
	v_mfma_f32_16x16x32_bf16 v[30:33], v[204:207], v[138:141], v[30:33]
	v_mfma_f32_16x16x32_bf16 v[86:89], v[196:199], v[154:157], v[86:89]
	v_mfma_f32_16x16x32_bf16 v[26:29], v[204:207], v[154:157], v[26:29]
	v_mfma_f32_16x16x32_bf16 v[82:85], v[196:199], v[162:165], v[82:85]
	v_mfma_f32_16x16x32_bf16 v[18:21], v[204:207], v[162:165], v[18:21]
	v_mfma_f32_16x16x32_bf16 v[90:93], v[196:199], v[188:191], v[90:93]
	v_mfma_f32_16x16x32_bf16 v[22:25], v[204:207], v[188:191], v[22:25]
	s_setprio 0
	s_add_i32 s42, 0, 0x18000
	v_add_u32_e32 v110, s42, v1
	s_barrier
	ds_read_b128 v[98:101], v110
	ds_read_b128 v[102:105], v110 offset:1024
	ds_read_b128 v[106:109], v110 offset:2048
	ds_read_b128 v[110:113], v110 offset:3072
	s_add_u32 s8, s8, 0x40000
	s_addc_u32 s9, s9, 0
	s_mov_b32 m0, s64
	v_lshl_add_u64 v[154:155], s[8:9], 0, v[176:177]
	ds_read_b128 v[126:129], v179 offset:32768
	ds_read_b128 v[138:141], v179 offset:33792
	ds_read_b128 v[150:153], v179 offset:34816
	ds_read_b128 v[158:161], v179 offset:35840
	ds_read_b128 v[162:165], v179 offset:36864
	ds_read_b128 v[184:187], v179 offset:37888
	ds_read_b128 v[188:191], v179 offset:38912
	ds_read_b128 v[192:195], v179 offset:39936
	global_load_lds_dwordx4 v[154:155], off
	v_lshl_add_u64 v[154:155], s[8:9], 0, v[172:173]
	s_mov_b32 m0, s65
	s_nop 0
	global_load_lds_dwordx4 v[154:155], off
	s_waitcnt lgkmcnt(8)
	s_barrier
	s_waitcnt lgkmcnt(0)
	s_setprio 1
	s_waitcnt lgkmcnt(0)
	v_mfma_f32_16x16x32_bf16 v[146:149], v[98:101], v[126:129], v[146:149]
	v_mfma_f32_16x16x32_bf16 v[46:49], v[106:109], v[126:129], v[46:49]
	v_mfma_f32_16x16x32_bf16 v[134:137], v[98:101], v[150:153], v[134:137]
	v_mfma_f32_16x16x32_bf16 v[38:41], v[106:109], v[150:153], v[38:41]
	v_mfma_f32_16x16x32_bf16 v[130:133], v[98:101], v[162:165], v[130:133]
	v_mfma_f32_16x16x32_bf16 v[34:37], v[106:109], v[162:165], v[34:37]
	v_mfma_f32_16x16x32_bf16 v[142:145], v[98:101], v[188:191], v[142:145]
	v_mfma_f32_16x16x32_bf16 v[42:45], v[106:109], v[188:191], v[42:45]
	v_mfma_f32_16x16x32_bf16 v[146:149], v[102:105], v[138:141], v[146:149]
	v_mfma_f32_16x16x32_bf16 v[46:49], v[110:113], v[138:141], v[46:49]
	v_mfma_f32_16x16x32_bf16 v[134:137], v[102:105], v[158:161], v[134:137]
	v_mfma_f32_16x16x32_bf16 v[38:41], v[110:113], v[158:161], v[38:41]
	v_mfma_f32_16x16x32_bf16 v[130:133], v[102:105], v[184:187], v[130:133]
	v_mfma_f32_16x16x32_bf16 v[34:37], v[110:113], v[184:187], v[34:37]
	v_mfma_f32_16x16x32_bf16 v[142:145], v[102:105], v[192:195], v[142:145]
	v_mfma_f32_16x16x32_bf16 v[42:45], v[110:113], v[192:195], v[42:45]
	s_setprio 0
	s_barrier
	s_add_i32 s8, 0, 0x1c000
	v_add_u32_e32 v154, s8, v1
	s_add_i32 s9, s42, s59
	ds_read_b128 v[196:199], v154
	ds_read_b128 v[200:203], v154 offset:1024
	ds_read_b128 v[204:207], v154 offset:2048
	ds_read_b128 v[208:211], v154 offset:3072
	v_lshl_add_u64 v[154:155], v[212:213], 0, s[38:39]
	s_mov_b32 m0, s9
	s_nop 0
	global_load_lds_dwordx4 v[154:155], off
	v_lshl_add_u64 v[154:155], v[214:215], 0, s[38:39]
	s_add_i32 m0, s9, 0x2000
	s_nop 0
	global_load_lds_dwordx4 v[154:155], off
	s_barrier
	s_waitcnt lgkmcnt(0)
	s_setprio 1
	s_waitcnt lgkmcnt(0)
	v_mfma_f32_16x16x32_bf16 v[154:157], v[196:199], v[126:129], v[166:169]
	v_mfma_f32_16x16x32_bf16 v[114:117], v[196:199], v[150:153], v[114:117]
	v_mfma_f32_16x16x32_bf16 v[166:169], v[200:203], v[138:141], v[154:157]
	v_mfma_f32_16x16x32_bf16 v[154:157], v[200:203], v[158:161], v[114:117]
	v_mfma_f32_16x16x32_bf16 v[114:117], v[196:199], v[162:165], v[118:121]
	v_mfma_f32_16x16x32_bf16 v[62:65], v[204:207], v[126:129], v[62:65]
	v_mfma_f32_16x16x32_bf16 v[54:57], v[204:207], v[150:153], v[54:57]
	v_mfma_f32_16x16x32_bf16 v[150:153], v[200:203], v[184:187], v[114:117]
	v_mfma_f32_16x16x32_bf16 v[50:53], v[204:207], v[162:165], v[50:53]
	v_mfma_f32_16x16x32_bf16 v[114:117], v[196:199], v[188:191], v[122:125]
	v_mfma_f32_16x16x32_bf16 v[58:61], v[204:207], v[188:191], v[58:61]
	v_mfma_f32_16x16x32_bf16 v[62:65], v[208:211], v[138:141], v[62:65]
	v_mfma_f32_16x16x32_bf16 v[54:57], v[208:211], v[158:161], v[54:57]
	v_mfma_f32_16x16x32_bf16 v[50:53], v[208:211], v[184:187], v[50:53]
	v_mfma_f32_16x16x32_bf16 v[158:161], v[200:203], v[192:195], v[114:117]
	v_mfma_f32_16x16x32_bf16 v[58:61], v[208:211], v[192:195], v[58:61]
	s_setprio 0
	s_mov_b32 m0, s71
	v_lshl_add_u64 v[192:193], v[216:217], 0, s[38:39]
	s_barrier
	ds_read_b128 v[114:117], v179 offset:49152
	ds_read_b128 v[118:121], v179 offset:50176
	ds_read_b128 v[122:125], v179 offset:51200
	ds_read_b128 v[126:129], v179 offset:52224
	ds_read_b128 v[138:141], v179 offset:53248
	ds_read_b128 v[162:165], v179 offset:54272
	ds_read_b128 v[184:187], v179 offset:55296
	ds_read_b128 v[188:191], v179 offset:56320
	global_load_lds_dwordx4 v[192:193], off
	v_lshl_add_u64 v[192:193], v[218:219], 0, s[38:39]
	s_mov_b32 m0, s72
	s_nop 0
	global_load_lds_dwordx4 v[192:193], off
	s_barrier
; __device__ __forceinline__ int otid(int wv) { int t; asm volatile("v_mbcnt_lo_u32_b32 %0, -1, 0\n\tv_mbcnt_hi_u32_b32 %0, -1, %0\n\tv_lshl_add_u32 %0, %1, 6, %0" : "=&v"(t) : "s"(wv)); return t; }
; #define PG8_STAGE(bufoff, gbase, voff) do { _Pragma("unroll") for (int _i = 0; _i < 2; ++_i) \
;         __builtin_amdgcn_global_load_lds((const unsigned*)((const char*)(gbase) + (voff)[_i]), (LAS unsigned*)(lds + (bufoff) + ldsw + _i * 8192), 16, 0, 0); } while (0)
; #define PG8_WAIT_V(n) asm volatile("s_waitcnt vmcnt(" #n ")" ::: "memory")
; #define PG8_WAIT_L(n) asm volatile("s_waitcnt lgkmcnt(" #n ")" ::: "memory")
; #define PG8_BAR __builtin_amdgcn_s_barrier()
; template <class Epi>
; __device__ __forceinline__ void gemm_phase(int wv, LAS unsigned char* lds, const Gemm g, const StaticOrder& S, const Epi& E) {
;     ...
;             PG8_BAR; PG8_WAIT_L(0); PG8_MMA(1, 0, At, B0); PG8_BAR; PG8_SCHED;
;             PG8_STAGE(PG8_SB(1, 1), b3 + hstepB, voffB);
;             PG8_WAIT_V(6); PG8_BAR; PG8_MMA(1, 1, At, B1); PG8_BAR;
;         }
;         { const int t2_ = otid(wv); E(acc, cur, wr, wc, t2_ & 15, (t2_ & 63) >> 4); }
;     __device__ __forceinline__ void operator()(const f32x4 (&acc)[2][2][4][2], const Unit& u, int wr, int wc, int fr, int fq) const {
;         asm volatile("" : "+v"(fr), "+v"(fq));
;         const int row0 = u.pm * BM + wr * 64 + fr, colt = u.pn * BM + wc * 32 + 8 * fq;
;         const int seq = seq_of_row(u.pm * BM);
;         const float* biasp = bias + (size_t)seq * NUP + colt; const float* cwp = cw + colt;
;         float rs[2][4];
; #pragma unroll
;         for (int ai = 0; ai < 2; ++ai)
; #pragma unroll
;             for (int m = 0; m < 4; ++m) rs[ai][m] = (float)ssin[row0 + ai * HALF + m * 16];
; #pragma unroll
;         for (int ai = 0; ai < 2; ++ai)
; #pragma unroll
;             for (int m = 0; m < 4; ++m) rs[ai][m] = __builtin_amdgcn_rsqf(rs[ai][m] * SSKI + EPSN);
; #pragma unroll
;         for (int n = 0; n < 2; ++n) {
;             f32x4 prm[2][5];
; #pragma unroll
;             for (int bj = 0; bj < 2; ++bj) { const int co = bj * HALF + 4 * n;
;                 prm[bj][0] = *(const f32x4*)(biasp + co); prm[bj][1] = *(const f32x4*)(cwp + co); prm[bj][2] = *(const f32x4*)(cwp + NUP + co); prm[bj][3] = *(const f32x4*)(cwp + 2 * NUP + co); prm[bj][4] = *(const f32x4*)(cwp + 3 * NUP + co); }
	s_waitcnt lgkmcnt(0)
	s_setprio 1
	s_waitcnt lgkmcnt(0)
	v_mfma_f32_16x16x32_bf16 v[78:81], v[98:101], v[114:117], v[78:81]
	v_mfma_f32_16x16x32_bf16 v[14:17], v[106:109], v[114:117], v[14:17]
	v_mfma_f32_16x16x32_bf16 v[70:73], v[98:101], v[122:125], v[70:73]
	v_mfma_f32_16x16x32_bf16 v[6:9], v[106:109], v[122:125], v[6:9]
	v_mfma_f32_16x16x32_bf16 v[66:69], v[98:101], v[138:141], v[66:69]
	v_mfma_f32_16x16x32_bf16 v[2:5], v[106:109], v[138:141], v[2:5]
	v_mfma_f32_16x16x32_bf16 v[74:77], v[98:101], v[184:187], v[74:77]
	v_mfma_f32_16x16x32_bf16 v[10:13], v[106:109], v[184:187], v[10:13]
	v_mfma_f32_16x16x32_bf16 v[78:81], v[102:105], v[118:121], v[78:81]
	v_mfma_f32_16x16x32_bf16 v[14:17], v[110:113], v[118:121], v[14:17]
	v_mfma_f32_16x16x32_bf16 v[70:73], v[102:105], v[126:129], v[70:73]
	v_mfma_f32_16x16x32_bf16 v[6:9], v[110:113], v[126:129], v[6:9]
	v_mfma_f32_16x16x32_bf16 v[66:69], v[102:105], v[162:165], v[66:69]
	v_mfma_f32_16x16x32_bf16 v[2:5], v[110:113], v[162:165], v[2:5]
	v_mfma_f32_16x16x32_bf16 v[74:77], v[102:105], v[188:191], v[74:77]
	v_mfma_f32_16x16x32_bf16 v[10:13], v[110:113], v[188:191], v[10:13]
	s_setprio 0
	s_barrier
	s_add_u32 s6, s6, 0x40080
	s_addc_u32 s7, s7, 0
	s_add_i32 s8, s8, s59
	v_lshl_add_u64 v[98:99], s[6:7], 0, v[174:175]
	s_mov_b32 m0, s8
	s_nop 0
	global_load_lds_dwordx4 v[98:99], off
	v_lshl_add_u64 v[98:99], s[6:7], 0, v[170:171]
	s_add_i32 m0, s8, 0x2000
	s_nop 0
	global_load_lds_dwordx4 v[98:99], off
	s_waitcnt vmcnt(6)
	s_barrier
	s_setprio 1
	v_mfma_f32_16x16x32_bf16 v[94:97], v[196:199], v[114:117], v[94:97]
	v_mfma_f32_16x16x32_bf16 v[30:33], v[204:207], v[114:117], v[30:33]
	v_mfma_f32_16x16x32_bf16 v[86:89], v[196:199], v[122:125], v[86:89]
	v_mfma_f32_16x16x32_bf16 v[26:29], v[204:207], v[122:125], v[26:29]
	v_mfma_f32_16x16x32_bf16 v[82:85], v[196:199], v[138:141], v[82:85]
	v_mfma_f32_16x16x32_bf16 v[18:21], v[204:207], v[138:141], v[18:21]
	v_mfma_f32_16x16x32_bf16 v[90:93], v[196:199], v[184:187], v[90:93]
	v_mfma_f32_16x16x32_bf16 v[22:25], v[204:207], v[184:187], v[22:25]
	v_mfma_f32_16x16x32_bf16 v[94:97], v[200:203], v[118:121], v[94:97]
	v_mfma_f32_16x16x32_bf16 v[30:33], v[208:211], v[118:121], v[30:33]
	v_mfma_f32_16x16x32_bf16 v[86:89], v[200:203], v[126:129], v[86:89]
	v_mfma_f32_16x16x32_bf16 v[26:29], v[208:211], v[126:129], v[26:29]
	v_mfma_f32_16x16x32_bf16 v[82:85], v[200:203], v[162:165], v[82:85]
	v_mfma_f32_16x16x32_bf16 v[18:21], v[208:211], v[162:165], v[18:21]
	v_mfma_f32_16x16x32_bf16 v[90:93], v[200:203], v[188:191], v[90:93]
	v_mfma_f32_16x16x32_bf16 v[22:25], v[208:211], v[188:191], v[22:25]
	s_setprio 0
	s_add_i32 s17, s17, 2
	s_add_u32 s4, s4, 0x100
	s_addc_u32 s5, s5, 0
	s_add_u32 s15, s15, 0x100
	s_addc_u32 s16, s16, 0
	s_cmp_gt_u32 s17, 13
	s_barrier
	s_cbranch_scc0 .LBB0_455
	v_mbcnt_lo_u32_b32 v246, -1, 0
	v_mbcnt_hi_u32_b32 v246, -1, v246
	s_lshl_b32 s4, s12, 8
	s_add_i32 s5, s4, s67
	v_and_b32_e32 v247, 15, v246
	v_bfe_u32 v248, v246, 4, 2
	s_cmpk_lt_u32 s4, 0x4000
	s_movk_i32 s7, 0x2c00
	s_cselect_b32 s7, 0x1600, s7
	s_cmp_gt_i32 s12, 31
	s_cselect_b32 s7, s7, 0
	s_lshl_b32 s7, s7, 2
	s_add_u32 s8, s48, s7
	s_addc_u32 s9, s49, 0
	s_add_u32 s10, s68, 0x5800
	s_addc_u32 s11, s69, 0
	s_add_u32 s14, s68, 0x10800
	s_addc_u32 s15, s69, 0
	v_lshl_add_u32 v249, v247, 2, s5
	v_lshlrev_b32_e32 v249, 3, v249
	s_lshl_b32 s6, s36, 8
	s_or_b32 s6, s6, s70
	v_lshl_add_u32 v244, v248, 3, s6
	v_lshlrev_b32_e32 v244, 2, v244
	global_load_dwordx4 v[184:187], v249, s[22:23]
	global_load_dwordx4 v[188:191], v249, s[22:23] offset:16
	global_load_dwordx4 v[192:195], v249, s[22:23] offset:1024
	global_load_dwordx4 v[196:199], v249, s[22:23] offset:1040
	s_lshl_b32 s42, s12, 2
	s_add_i32 s42, s42, s66
	s_mul_i32 s16, s42, 0x16000
	s_mul_hi_u32 s17, s42, 0x16000
	s_add_u32 s54, s50, s16
	s_addc_u32 s55, s51, s17
	s_mul_i32 s16, s5, 0x1600
	s_mul_hi_u32 s17, s5, 0x1600
	s_add_u32 s74, s90, s16
	s_addc_u32 s75, s91, s17
	s_lshl_b32 s16, s36, 8
	s_lshl_b32 s17, s70, 1
	s_add_i32 s16, s16, s17
	s_add_u32 s74, s74, s16
	s_addc_u32 s75, s75, 0
	s_add_u32 s12, s68, 0xb000
	s_addc_u32 s13, s69, 0
	global_load_dwordx4 v[98:101], v244, s[8:9]
	global_load_dwordx4 v[102:105], v244, s[68:69]
	global_load_dwordx4 v[106:109], v244, s[10:11]
	global_load_dwordx4 v[110:113], v244, s[12:13]
	global_load_dwordx4 v[114:117], v244, s[14:15]
	global_load_dwordx4 v[118:121], v244, s[8:9] offset:512
	global_load_dwordx4 v[122:125], v244, s[68:69] offset:512
	global_load_dwordx4 v[126:129], v244, s[10:11] offset:512
	global_load_dwordx4 v[138:141], v244, s[12:13] offset:512
	global_load_dwordx4 v[162:165], v244, s[14:15] offset:512
	v_cmp_eq_u32_e64 s[4:5], 0, v247
	v_cmp_eq_u32_e64 s[6:7], 15, v247
	v_mul_u32_u24_e32 v245, 0x5800, v247
	v_lshl_add_u32 v245, v248, 4, v245
	v_mov_b32_e32 v240, 0xbfb8aa3b
	v_mov_b32_e32 v241, 0xbfb8aa3b
	s_waitcnt vmcnt(0)
;     __device__ __forceinline__ void operator()(const f32x4 (&acc)[2][2][4][2], const Unit& u, int wr, int wc, int fr, int fq) const {
;     ...
;             for (int m = 0; m < 4; ++m) rs[ai][m] = __builtin_amdgcn_rsqf(rs[ai][m] * SSKI + EPSN);
; #pragma unroll
;         for (int n = 0; n < 2; ++n) {
;             f32x4 prm[2][5];
; #pragma unroll
;             for (int bj = 0; bj < 2; ++bj) { const int co = bj * HALF + 4 * n;
;                 prm[bj][0] = *(const f32x4*)(biasp + co); prm[bj][1] = *(const f32x4*)(cwp + co); prm[bj][2] = *(const f32x4*)(cwp + NUP + co); prm[bj][3] = *(const f32x4*)(cwp + 2 * NUP + co); prm[bj][4] = *(const f32x4*)(cwp + 3 * NUP + co); }
; #pragma unroll
;             for (int ai = 0; ai < 2; ++ai) {
;                 float* ep = edge + (size_t)(u.pm * 4 + ai * 2 + wr) * 4 * NUP + colt;
;                 f32x4 SG[4];
; #pragma unroll
;                 for (int bjr = 0; bjr < 2; ++bjr) { const int bj = 1 - bjr; const int co = bj * HALF + 4 * n;
;                     f32x4 U[4];
; #pragma unroll
;                     for (int m = 0; m < 4; ++m) U[m] = acc[ai][bj][m][n] * rs[ai][m] + prm[bj][0];
;                     if (fr < 2) *(f32x4*)(ep + (size_t)fr * NUP + co) = U[0];
;                     if (fr >= 14) *(f32x4*)(ep + (size_t)(fr - 12) * NUP + co) = U[3];
; #pragma unroll
;                     for (int m = 0; m < 4; ++m) { const f32x4 sp = (fr == 15 && m > 0) ? U[m > 0 ? m - 1 : 0] : U[m]; const f32x4 sn = (fr == 0 && m < 3) ? U[m < 3 ? m + 1 : 3] : U[m];
;                         f32x4 pv, nv;
; #pragma unroll
;                         for (int j = 0; j < 4; ++j) { pv[j] = __int_as_float(__builtin_amdgcn_update_dpp(0, __float_as_int(sp[j]), 0x121, 0xf, 0xf, false)); nv[j] = __int_as_float(__builtin_amdgcn_update_dpp(0, __float_as_int(sn[j]), 0x12F, 0xf, 0xf, false)); }
;                         const f32x4 R = prm[bj][1] * pv + prm[bj][2] * U[m] + prm[bj][3] * nv + prm[bj][4];
;                         if (bj == 1) {
; #pragma unroll
;                             for (int j = 0; j < 4; ++j) SG[m][j] = R[j] * __builtin_amdgcn_rcpf(1.0f + __expf(-R[j])); }
	v_cvt_f32_u32_e32 v242, v185
	v_cvt_f32_u32_e32 v243, v184
	v_fmamk_f32 v242, v242, 0x4f800000, v243
	v_fmamk_f32 v242, v242, 0x30800000, v251
	v_rsq_f32_e32 v224, v242
	v_cvt_f32_u32_e32 v242, v187
	v_cvt_f32_u32_e32 v243, v186
	v_fmamk_f32 v242, v242, 0x4f800000, v243
	v_fmamk_f32 v242, v242, 0x30800000, v251
	v_rsq_f32_e32 v225, v242
	v_cvt_f32_u32_e32 v242, v189
	v_cvt_f32_u32_e32 v243, v188
	v_fmamk_f32 v242, v242, 0x4f800000, v243
	v_fmamk_f32 v242, v242, 0x30800000, v251
	v_rsq_f32_e32 v226, v242
	v_cvt_f32_u32_e32 v242, v191
	v_cvt_f32_u32_e32 v243, v190
	v_fmamk_f32 v242, v242, 0x4f800000, v243
	v_fmamk_f32 v242, v242, 0x30800000, v251
	v_rsq_f32_e32 v227, v242
	v_cvt_f32_u32_e32 v242, v193
	v_cvt_f32_u32_e32 v243, v192
	v_fmamk_f32 v242, v242, 0x4f800000, v243
	v_fmamk_f32 v242, v242, 0x30800000, v251
	v_rsq_f32_e32 v228, v242
	v_cvt_f32_u32_e32 v242, v195
	v_cvt_f32_u32_e32 v243, v194
	v_fmamk_f32 v242, v242, 0x4f800000, v243
	v_fmamk_f32 v242, v242, 0x30800000, v251
	v_rsq_f32_e32 v229, v242
	v_cvt_f32_u32_e32 v242, v197
	v_cvt_f32_u32_e32 v243, v196
	v_fmamk_f32 v242, v242, 0x4f800000, v243
	v_fmamk_f32 v242, v242, 0x30800000, v251
	v_rsq_f32_e32 v230, v242
	v_cvt_f32_u32_e32 v242, v199
	v_cvt_f32_u32_e32 v243, v198
	v_fmamk_f32 v242, v242, 0x4f800000, v243
	v_fmamk_f32 v242, v242, 0x30800000, v251
	v_rsq_f32_e32 v231, v242
	global_load_dwordx4 v[184:187], v244, s[8:9] offset:16
	global_load_dwordx4 v[188:191], v244, s[68:69] offset:16
	global_load_dwordx4 v[192:195], v244, s[10:11] offset:16
	global_load_dwordx4 v[196:199], v244, s[12:13] offset:16
	global_load_dwordx4 v[200:203], v244, s[14:15] offset:16
	global_load_dwordx4 v[204:207], v244, s[8:9] offset:528
	global_load_dwordx4 v[208:211], v244, s[68:69] offset:528
	global_load_dwordx4 v[212:215], v244, s[10:11] offset:528
	global_load_dwordx4 v[216:219], v244, s[12:13] offset:528
	global_load_dwordx4 v[220:223], v244, s[14:15] offset:528
	v_pk_fma_f32 v[166:167], v[166:167], v[224:225], v[118:119] op_sel_hi:[1,0,1]
	v_pk_fma_f32 v[168:169], v[168:169], v[224:225], v[120:121] op_sel_hi:[1,0,1]
	v_pk_fma_f32 v[154:155], v[154:155], v[224:225], v[118:119] op_sel:[0,1,0] op_sel_hi:[1,1,1]
	v_pk_fma_f32 v[156:157], v[156:157], v[224:225], v[120:121] op_sel:[0,1,0] op_sel_hi:[1,1,1]
	v_pk_fma_f32 v[150:151], v[150:151], v[226:227], v[118:119] op_sel_hi:[1,0,1]
	v_pk_fma_f32 v[152:153], v[152:153], v[226:227], v[120:121] op_sel_hi:[1,0,1]
	v_pk_fma_f32 v[158:159], v[158:159], v[226:227], v[118:119] op_sel:[0,1,0] op_sel_hi:[1,1,1]
	v_pk_fma_f32 v[160:161], v[160:161], v[226:227], v[120:121] op_sel:[0,1,0] op_sel_hi:[1,1,1]
	s_mov_b64 exec, s[4:5]
	global_store_dwordx4 v244, v[166:169], s[54:55] offset:512
	s_add_u32 s16, s54, 0x5800
	s_addc_u32 s17, s55, 0
	global_store_dwordx4 v244, v[154:157], s[16:17] offset:512
	s_mov_b64 exec, s[6:7]
	s_add_u32 s56, s54, 0xb000
	s_addc_u32 s57, s55, 0
	global_store_dwordx4 v244, v[150:153], s[56:57] offset:512
	s_add_u32 s16, s54, 0x10800
	s_addc_u32 s17, s55, 0
	global_store_dwordx4 v244, v[158:161], s[16:17] offset:512
	s_mov_b64 exec, -1
	v_pk_fma_f32 v[232:233], v[126:127], v[166:167], v[162:163]
	v_pk_fma_f32 v[234:235], v[126:127], v[154:155], v[162:163]
	v_pk_fma_f32 v[236:237], v[126:127], v[150:151], v[162:163]
	v_pk_fma_f32 v[238:239], v[126:127], v[158:159], v[162:163]
	v_pk_fma_f32 v[234:235], v[122:123], v[166:167], v[234:235]
	v_pk_fma_f32 v[236:237], v[122:123], v[154:155], v[236:237]
	v_pk_fma_f32 v[238:239], v[122:123], v[150:151], v[238:239]
	v_pk_fma_f32 v[232:233], v[138:139], v[154:155], v[232:233]
	v_pk_fma_f32 v[234:235], v[138:139], v[150:151], v[234:235]
	v_pk_fma_f32 v[236:237], v[138:139], v[158:159], v[236:237]
	v_fmac_f32_dpp v232, v158, v122 row_ror:1 row_mask:0xf bank_mask:0xf
	v_fmac_f32_dpp v233, v159, v123 row_ror:1 row_mask:0xf bank_mask:0xf
	v_fmac_f32_dpp v238, v166, v138 row_ror:15 row_mask:0xf bank_mask:0xf
	v_fmac_f32_dpp v239, v167, v139 row_ror:15 row_mask:0xf bank_mask:0xf
	v_pk_mul_f32 v[166:167], v[232:233], v[240:241]
	v_pk_mul_f32 v[154:155], v[234:235], v[240:241]
	v_pk_mul_f32 v[150:151], v[236:237], v[240:241]
	v_pk_mul_f32 v[158:159], v[238:239], v[240:241]
	v_exp_f32_e32 v166, v166
	v_exp_f32_e32 v167, v167
	v_exp_f32_e32 v154, v154
	v_exp_f32_e32 v155, v155
	v_exp_f32_e32 v150, v150
	v_exp_f32_e32 v151, v151
	v_exp_f32_e32 v158, v158
	v_exp_f32_e32 v159, v159
	v_pk_add_f32 v[166:167], v[166:167], 1.0 op_sel_hi:[1,0]
	v_pk_add_f32 v[154:155], v[154:155], 1.0 op_sel_hi:[1,0]
	v_pk_add_f32 v[150:151], v[150:151], 1.0 op_sel_hi:[1,0]
	v_pk_add_f32 v[158:159], v[158:159], 1.0 op_sel_hi:[1,0]
	v_rcp_f32_e32 v166, v166
	v_rcp_f32_e32 v167, v167
	v_rcp_f32_e32 v154, v154
	v_rcp_f32_e32 v155, v155
	v_rcp_f32_e32 v150, v150
	v_rcp_f32_e32 v151, v151
	v_rcp_f32_e32 v158, v158
	v_rcp_f32_e32 v159, v159
	v_pk_mul_f32 v[166:167], v[232:233], v[166:167]
	v_pk_mul_f32 v[154:155], v[234:235], v[154:155]
	v_pk_mul_f32 v[150:151], v[236:237], v[150:151]
	v_pk_mul_f32 v[158:159], v[238:239], v[158:159]
	v_pk_fma_f32 v[232:233], v[128:129], v[168:169], v[164:165]
	v_pk_fma_f32 v[234:235], v[128:129], v[156:157], v[164:165]
	v_pk_fma_f32 v[236:237], v[128:129], v[152:153], v[164:165]
	v_pk_fma_f32 v[238:239], v[128:129], v[160:161], v[164:165]
	v_pk_fma_f32 v[234:235], v[124:125], v[168:169], v[234:235]
	v_pk_fma_f32 v[236:237], v[124:125], v[156:157], v[236:237]
	v_pk_fma_f32 v[238:239], v[124:125], v[152:153], v[238:239]
	v_pk_fma_f32 v[232:233], v[140:141], v[156:157], v[232:233]
	v_pk_fma_f32 v[234:235], v[140:141], v[152:153], v[234:235]
	v_pk_fma_f32 v[236:237], v[140:141], v[160:161], v[236:237]
; __device__ __forceinline__ unsigned cvt_pk_bf16_asm(float lo, float hi) { unsigned r; asm volatile("v_cvt_pk_bf16_f32 %0, %1, %2" : "=v"(r) : "v"(lo), "v"(hi)); return r; }
;     __device__ __forceinline__ void operator()(const f32x4 (&acc)[2][2][4][2], const Unit& u, int wr, int wc, int fr, int fq) const {
;     ...
;                 for (int bjr = 0; bjr < 2; ++bjr) { const int bj = 1 - bjr; const int co = bj * HALF + 4 * n;
;                     f32x4 U[4];
; #pragma unroll
;                     for (int m = 0; m < 4; ++m) U[m] = acc[ai][bj][m][n] * rs[ai][m] + prm[bj][0];
;                     if (fr < 2) *(f32x4*)(ep + (size_t)fr * NUP + co) = U[0];
;                     if (fr >= 14) *(f32x4*)(ep + (size_t)(fr - 12) * NUP + co) = U[3];
; #pragma unroll
;                     for (int m = 0; m < 4; ++m) { const f32x4 sp = (fr == 15 && m > 0) ? U[m > 0 ? m - 1 : 0] : U[m]; const f32x4 sn = (fr == 0 && m < 3) ? U[m < 3 ? m + 1 : 3] : U[m];
;                         f32x4 pv, nv;
; #pragma unroll
;                         for (int j = 0; j < 4; ++j) { pv[j] = __int_as_float(__builtin_amdgcn_update_dpp(0, __float_as_int(sp[j]), 0x121, 0xf, 0xf, false)); nv[j] = __int_as_float(__builtin_amdgcn_update_dpp(0, __float_as_int(sn[j]), 0x12F, 0xf, 0xf, false)); }
;                         const f32x4 R = prm[bj][1] * pv + prm[bj][2] * U[m] + prm[bj][3] * nv + prm[bj][4];
;                         if (bj == 1) {
; #pragma unroll
;                             for (int j = 0; j < 4; ++j) SG[m][j] = R[j] * __builtin_amdgcn_rcpf(1.0f + __expf(-R[j])); }
;                         else { const int r = row0 + ai * HALF + m * 16; const bool skip = (m == 0 && fr == 0) || (m == 3 && fr == 15);
;                             const f32x4 o = R * SG[m]; u32x2 w; w.x = cvt_pk_bf16_asm(o[0], o[1]); w.y = cvt_pk_bf16_asm(o[2], o[3]);
;                             if (!skip) *(u32x2*)(act + (size_t)r * FFD + u.pn * 128 + wc * 32 + 8 * fq + 4 * n) = w; } } } }
	v_fmac_f32_dpp v232, v160, v124 row_ror:1 row_mask:0xf bank_mask:0xf
	v_fmac_f32_dpp v233, v161, v125 row_ror:1 row_mask:0xf bank_mask:0xf
	v_fmac_f32_dpp v238, v168, v140 row_ror:15 row_mask:0xf bank_mask:0xf
	v_fmac_f32_dpp v239, v169, v141 row_ror:15 row_mask:0xf bank_mask:0xf
	v_pk_mul_f32 v[168:169], v[232:233], v[240:241]
	v_pk_mul_f32 v[156:157], v[234:235], v[240:241]
	v_pk_mul_f32 v[152:153], v[236:237], v[240:241]
	v_pk_mul_f32 v[160:161], v[238:239], v[240:241]
	v_exp_f32_e32 v168, v168
	v_exp_f32_e32 v169, v169
	v_exp_f32_e32 v156, v156
	v_exp_f32_e32 v157, v157
	v_exp_f32_e32 v152, v152
	v_exp_f32_e32 v153, v153
	v_exp_f32_e32 v160, v160
	v_exp_f32_e32 v161, v161
	v_pk_add_f32 v[168:169], v[168:169], 1.0 op_sel_hi:[1,0]
	v_pk_add_f32 v[156:157], v[156:157], 1.0 op_sel_hi:[1,0]
	v_pk_add_f32 v[152:153], v[152:153], 1.0 op_sel_hi:[1,0]
	v_pk_add_f32 v[160:161], v[160:161], 1.0 op_sel_hi:[1,0]
	v_rcp_f32_e32 v168, v168
	v_rcp_f32_e32 v169, v169
	v_rcp_f32_e32 v156, v156
	v_rcp_f32_e32 v157, v157
	v_rcp_f32_e32 v152, v152
	v_rcp_f32_e32 v153, v153
	v_rcp_f32_e32 v160, v160
	v_rcp_f32_e32 v161, v161
	v_pk_mul_f32 v[168:169], v[232:233], v[168:169]
	v_pk_mul_f32 v[156:157], v[234:235], v[156:157]
	v_pk_mul_f32 v[152:153], v[236:237], v[152:153]
	v_pk_mul_f32 v[160:161], v[238:239], v[160:161]
	v_pk_fma_f32 v[146:147], v[146:147], v[224:225], v[98:99] op_sel_hi:[1,0,1]
	v_pk_fma_f32 v[148:149], v[148:149], v[224:225], v[100:101] op_sel_hi:[1,0,1]
	v_pk_fma_f32 v[134:135], v[134:135], v[224:225], v[98:99] op_sel:[0,1,0] op_sel_hi:[1,1,1]
	v_pk_fma_f32 v[136:137], v[136:137], v[224:225], v[100:101] op_sel:[0,1,0] op_sel_hi:[1,1,1]
	v_pk_fma_f32 v[130:131], v[130:131], v[226:227], v[98:99] op_sel_hi:[1,0,1]
	v_pk_fma_f32 v[132:133], v[132:133], v[226:227], v[100:101] op_sel_hi:[1,0,1]
	v_pk_fma_f32 v[142:143], v[142:143], v[226:227], v[98:99] op_sel:[0,1,0] op_sel_hi:[1,1,1]
	v_pk_fma_f32 v[144:145], v[144:145], v[226:227], v[100:101] op_sel:[0,1,0] op_sel_hi:[1,1,1]
	s_mov_b64 exec, s[4:5]
	global_store_dwordx4 v244, v[146:149], s[54:55]
	s_add_u32 s16, s54, 0x5800
	s_addc_u32 s17, s55, 0
	global_store_dwordx4 v244, v[134:137], s[16:17]
	s_mov_b64 exec, s[6:7]
	s_add_u32 s56, s54, 0xb000
	s_addc_u32 s57, s55, 0
	global_store_dwordx4 v244, v[130:133], s[56:57]
	s_add_u32 s16, s54, 0x10800
	s_addc_u32 s17, s55, 0
	global_store_dwordx4 v244, v[142:145], s[16:17]
	s_mov_b64 exec, -1
	v_pk_fma_f32 v[232:233], v[106:107], v[146:147], v[114:115]
	v_pk_fma_f32 v[234:235], v[106:107], v[134:135], v[114:115]
	v_pk_fma_f32 v[236:237], v[106:107], v[130:131], v[114:115]
	v_pk_fma_f32 v[238:239], v[106:107], v[142:143], v[114:115]
	v_pk_fma_f32 v[234:235], v[102:103], v[146:147], v[234:235]
	v_pk_fma_f32 v[236:237], v[102:103], v[134:135], v[236:237]
	v_pk_fma_f32 v[238:239], v[102:103], v[130:131], v[238:239]
	v_pk_fma_f32 v[232:233], v[110:111], v[134:135], v[232:233]
	v_pk_fma_f32 v[234:235], v[110:111], v[130:131], v[234:235]
	v_pk_fma_f32 v[236:237], v[110:111], v[142:143], v[236:237]
	v_fmac_f32_dpp v232, v142, v102 row_ror:1 row_mask:0xf bank_mask:0xf
	v_fmac_f32_dpp v233, v143, v103 row_ror:1 row_mask:0xf bank_mask:0xf
	v_fmac_f32_dpp v238, v146, v110 row_ror:15 row_mask:0xf bank_mask:0xf
	v_fmac_f32_dpp v239, v147, v111 row_ror:15 row_mask:0xf bank_mask:0xf
	v_pk_mul_f32 v[232:233], v[232:233], v[166:167]
	v_pk_mul_f32 v[234:235], v[234:235], v[154:155]
	v_pk_mul_f32 v[236:237], v[236:237], v[150:151]
	v_pk_mul_f32 v[238:239], v[238:239], v[158:159]
	v_cvt_pk_bf16_f32 v146, v232, v233
	v_cvt_pk_bf16_f32 v134, v234, v235
	v_cvt_pk_bf16_f32 v130, v236, v237
	v_cvt_pk_bf16_f32 v142, v238, v239
	v_pk_fma_f32 v[232:233], v[108:109], v[148:149], v[116:117]
	v_pk_fma_f32 v[234:235], v[108:109], v[136:137], v[116:117]
	v_pk_fma_f32 v[236:237], v[108:109], v[132:133], v[116:117]
	v_pk_fma_f32 v[238:239], v[108:109], v[144:145], v[116:117]
	v_pk_fma_f32 v[234:235], v[104:105], v[148:149], v[234:235]
	v_pk_fma_f32 v[236:237], v[104:105], v[136:137], v[236:237]
	v_pk_fma_f32 v[238:239], v[104:105], v[132:133], v[238:239]
	v_pk_fma_f32 v[232:233], v[112:113], v[136:137], v[232:233]
	v_pk_fma_f32 v[234:235], v[112:113], v[132:133], v[234:235]
	v_pk_fma_f32 v[236:237], v[112:113], v[144:145], v[236:237]
	v_fmac_f32_dpp v232, v144, v104 row_ror:1 row_mask:0xf bank_mask:0xf
	v_fmac_f32_dpp v233, v145, v105 row_ror:1 row_mask:0xf bank_mask:0xf
	v_fmac_f32_dpp v238, v148, v112 row_ror:15 row_mask:0xf bank_mask:0xf
	v_fmac_f32_dpp v239, v149, v113 row_ror:15 row_mask:0xf bank_mask:0xf
	v_pk_mul_f32 v[232:233], v[232:233], v[168:169]
	v_pk_mul_f32 v[234:235], v[234:235], v[156:157]
	v_pk_mul_f32 v[236:237], v[236:237], v[152:153]
	v_pk_mul_f32 v[238:239], v[238:239], v[160:161]
	v_cvt_pk_bf16_f32 v147, v232, v233
	v_cvt_pk_bf16_f32 v135, v234, v235
	v_cvt_pk_bf16_f32 v131, v236, v237
	v_cvt_pk_bf16_f32 v143, v238, v239
	s_add_u32 s54, s54, 0x2c000
	s_addc_u32 s55, s55, 0
	v_pk_fma_f32 v[94:95], v[94:95], v[228:229], v[118:119] op_sel_hi:[1,0,1]
	v_pk_fma_f32 v[96:97], v[96:97], v[228:229], v[120:121] op_sel_hi:[1,0,1]
	v_pk_fma_f32 v[86:87], v[86:87], v[228:229], v[118:119] op_sel:[0,1,0] op_sel_hi:[1,1,1]
	v_pk_fma_f32 v[88:89], v[88:89], v[228:229], v[120:121] op_sel:[0,1,0] op_sel_hi:[1,1,1]
	v_pk_fma_f32 v[82:83], v[82:83], v[230:231], v[118:119] op_sel_hi:[1,0,1]
	v_pk_fma_f32 v[84:85], v[84:85], v[230:231], v[120:121] op_sel_hi:[1,0,1]
	v_pk_fma_f32 v[90:91], v[90:91], v[230:231], v[118:119] op_sel:[0,1,0] op_sel_hi:[1,1,1]
	v_pk_fma_f32 v[92:93], v[92:93], v[230:231], v[120:121] op_sel:[0,1,0] op_sel_hi:[1,1,1]
	s_mov_b64 exec, s[4:5]
;     __device__ __forceinline__ void operator()(const f32x4 (&acc)[2][2][4][2], const Unit& u, int wr, int wc, int fr, int fq) const {
;     ...
;                 for (int bjr = 0; bjr < 2; ++bjr) { const int bj = 1 - bjr; const int co = bj * HALF + 4 * n;
;                     f32x4 U[4];
; #pragma unroll
;                     for (int m = 0; m < 4; ++m) U[m] = acc[ai][bj][m][n] * rs[ai][m] + prm[bj][0];
;                     if (fr < 2) *(f32x4*)(ep + (size_t)fr * NUP + co) = U[0];
;                     if (fr >= 14) *(f32x4*)(ep + (size_t)(fr - 12) * NUP + co) = U[3];
; #pragma unroll
;                     for (int m = 0; m < 4; ++m) { const f32x4 sp = (fr == 15 && m > 0) ? U[m > 0 ? m - 1 : 0] : U[m]; const f32x4 sn = (fr == 0 && m < 3) ? U[m < 3 ? m + 1 : 3] : U[m];
;                         f32x4 pv, nv;
; #pragma unroll
;                         for (int j = 0; j < 4; ++j) { pv[j] = __int_as_float(__builtin_amdgcn_update_dpp(0, __float_as_int(sp[j]), 0x121, 0xf, 0xf, false)); nv[j] = __int_as_float(__builtin_amdgcn_update_dpp(0, __float_as_int(sn[j]), 0x12F, 0xf, 0xf, false)); }
;                         const f32x4 R = prm[bj][1] * pv + prm[bj][2] * U[m] + prm[bj][3] * nv + prm[bj][4];
;                         if (bj == 1) {
; #pragma unroll
;                             for (int j = 0; j < 4; ++j) SG[m][j] = R[j] * __builtin_amdgcn_rcpf(1.0f + __expf(-R[j])); }
	global_store_dwordx4 v244, v[94:97], s[54:55] offset:512
	s_add_u32 s16, s54, 0x5800
	s_addc_u32 s17, s55, 0
	global_store_dwordx4 v244, v[86:89], s[16:17] offset:512
	s_mov_b64 exec, s[6:7]
	s_add_u32 s56, s54, 0xb000
	s_addc_u32 s57, s55, 0
	global_store_dwordx4 v244, v[82:85], s[56:57] offset:512
	s_add_u32 s16, s54, 0x10800
	s_addc_u32 s17, s55, 0
	global_store_dwordx4 v244, v[90:93], s[16:17] offset:512
	s_mov_b64 exec, -1
	v_pk_fma_f32 v[232:233], v[126:127], v[94:95], v[162:163]
	v_pk_fma_f32 v[234:235], v[126:127], v[86:87], v[162:163]
	v_pk_fma_f32 v[236:237], v[126:127], v[82:83], v[162:163]
	v_pk_fma_f32 v[238:239], v[126:127], v[90:91], v[162:163]
	v_pk_fma_f32 v[234:235], v[122:123], v[94:95], v[234:235]
	v_pk_fma_f32 v[236:237], v[122:123], v[86:87], v[236:237]
	v_pk_fma_f32 v[238:239], v[122:123], v[82:83], v[238:239]
	v_pk_fma_f32 v[232:233], v[138:139], v[86:87], v[232:233]
	v_pk_fma_f32 v[234:235], v[138:139], v[82:83], v[234:235]
	v_pk_fma_f32 v[236:237], v[138:139], v[90:91], v[236:237]
	v_fmac_f32_dpp v232, v90, v122 row_ror:1 row_mask:0xf bank_mask:0xf
	v_fmac_f32_dpp v233, v91, v123 row_ror:1 row_mask:0xf bank_mask:0xf
	v_fmac_f32_dpp v238, v94, v138 row_ror:15 row_mask:0xf bank_mask:0xf
	v_fmac_f32_dpp v239, v95, v139 row_ror:15 row_mask:0xf bank_mask:0xf
	v_pk_mul_f32 v[94:95], v[232:233], v[240:241]
	v_pk_mul_f32 v[86:87], v[234:235], v[240:241]
	v_pk_mul_f32 v[82:83], v[236:237], v[240:241]
	v_pk_mul_f32 v[90:91], v[238:239], v[240:241]
	v_exp_f32_e32 v94, v94
	v_exp_f32_e32 v95, v95
	v_exp_f32_e32 v86, v86
	v_exp_f32_e32 v87, v87
	v_exp_f32_e32 v82, v82
	v_exp_f32_e32 v83, v83
	v_exp_f32_e32 v90, v90
	v_exp_f32_e32 v91, v91
	v_pk_add_f32 v[94:95], v[94:95], 1.0 op_sel_hi:[1,0]
	v_pk_add_f32 v[86:87], v[86:87], 1.0 op_sel_hi:[1,0]
	v_pk_add_f32 v[82:83], v[82:83], 1.0 op_sel_hi:[1,0]
	v_pk_add_f32 v[90:91], v[90:91], 1.0 op_sel_hi:[1,0]
	v_rcp_f32_e32 v94, v94
	v_rcp_f32_e32 v95, v95
	v_rcp_f32_e32 v86, v86
	v_rcp_f32_e32 v87, v87
	v_rcp_f32_e32 v82, v82
	v_rcp_f32_e32 v83, v83
	v_rcp_f32_e32 v90, v90
	v_rcp_f32_e32 v91, v91
	v_pk_mul_f32 v[94:95], v[232:233], v[94:95]
	v_pk_mul_f32 v[86:87], v[234:235], v[86:87]
	v_pk_mul_f32 v[82:83], v[236:237], v[82:83]
	v_pk_mul_f32 v[90:91], v[238:239], v[90:91]
	v_pk_fma_f32 v[232:233], v[128:129], v[96:97], v[164:165]
	v_pk_fma_f32 v[234:235], v[128:129], v[88:89], v[164:165]
	v_pk_fma_f32 v[236:237], v[128:129], v[84:85], v[164:165]
	v_pk_fma_f32 v[238:239], v[128:129], v[92:93], v[164:165]
	v_pk_fma_f32 v[234:235], v[124:125], v[96:97], v[234:235]
	v_pk_fma_f32 v[236:237], v[124:125], v[88:89], v[236:237]
	v_pk_fma_f32 v[238:239], v[124:125], v[84:85], v[238:239]
	v_pk_fma_f32 v[232:233], v[140:141], v[88:89], v[232:233]
	v_pk_fma_f32 v[234:235], v[140:141], v[84:85], v[234:235]
	v_pk_fma_f32 v[236:237], v[140:141], v[92:93], v[236:237]
	v_fmac_f32_dpp v232, v92, v124 row_ror:1 row_mask:0xf bank_mask:0xf
	v_fmac_f32_dpp v233, v93, v125 row_ror:1 row_mask:0xf bank_mask:0xf
	v_fmac_f32_dpp v238, v96, v140 row_ror:15 row_mask:0xf bank_mask:0xf
	v_fmac_f32_dpp v239, v97, v141 row_ror:15 row_mask:0xf bank_mask:0xf
	v_pk_mul_f32 v[96:97], v[232:233], v[240:241]
	v_pk_mul_f32 v[88:89], v[234:235], v[240:241]
	v_pk_mul_f32 v[84:85], v[236:237], v[240:241]
	v_pk_mul_f32 v[92:93], v[238:239], v[240:241]
	v_exp_f32_e32 v96, v96
	v_exp_f32_e32 v97, v97
	v_exp_f32_e32 v88, v88
	v_exp_f32_e32 v89, v89
	v_exp_f32_e32 v84, v84
	v_exp_f32_e32 v85, v85
	v_exp_f32_e32 v92, v92
	v_exp_f32_e32 v93, v93
	v_pk_add_f32 v[96:97], v[96:97], 1.0 op_sel_hi:[1,0]
	v_pk_add_f32 v[88:89], v[88:89], 1.0 op_sel_hi:[1,0]
	v_pk_add_f32 v[84:85], v[84:85], 1.0 op_sel_hi:[1,0]
	v_pk_add_f32 v[92:93], v[92:93], 1.0 op_sel_hi:[1,0]
	v_rcp_f32_e32 v96, v96
	v_rcp_f32_e32 v97, v97
	v_rcp_f32_e32 v88, v88
	v_rcp_f32_e32 v89, v89
	v_rcp_f32_e32 v84, v84
	v_rcp_f32_e32 v85, v85
	v_rcp_f32_e32 v92, v92
	v_rcp_f32_e32 v93, v93
	v_pk_mul_f32 v[96:97], v[232:233], v[96:97]
	v_pk_mul_f32 v[88:89], v[234:235], v[88:89]
	v_pk_mul_f32 v[84:85], v[236:237], v[84:85]
	v_pk_mul_f32 v[92:93], v[238:239], v[92:93]
	v_pk_fma_f32 v[78:79], v[78:79], v[228:229], v[98:99] op_sel_hi:[1,0,1]
	v_pk_fma_f32 v[80:81], v[80:81], v[228:229], v[100:101] op_sel_hi:[1,0,1]
	v_pk_fma_f32 v[70:71], v[70:71], v[228:229], v[98:99] op_sel:[0,1,0] op_sel_hi:[1,1,1]
	v_pk_fma_f32 v[72:73], v[72:73], v[228:229], v[100:101] op_sel:[0,1,0] op_sel_hi:[1,1,1]
	v_pk_fma_f32 v[66:67], v[66:67], v[230:231], v[98:99] op_sel_hi:[1,0,1]
	v_pk_fma_f32 v[68:69], v[68:69], v[230:231], v[100:101] op_sel_hi:[1,0,1]
	v_pk_fma_f32 v[74:75], v[74:75], v[230:231], v[98:99] op_sel:[0,1,0] op_sel_hi:[1,1,1]
	v_pk_fma_f32 v[76:77], v[76:77], v[230:231], v[100:101] op_sel:[0,1,0] op_sel_hi:[1,1,1]
	s_mov_b64 exec, s[4:5]
	global_store_dwordx4 v244, v[78:81], s[54:55]
	s_add_u32 s16, s54, 0x5800
	s_addc_u32 s17, s55, 0
	global_store_dwordx4 v244, v[70:73], s[16:17]
	s_mov_b64 exec, s[6:7]
	s_add_u32 s56, s54, 0xb000
	s_addc_u32 s57, s55, 0
	global_store_dwordx4 v244, v[66:69], s[56:57]
	s_add_u32 s16, s54, 0x10800
	s_addc_u32 s17, s55, 0
	global_store_dwordx4 v244, v[74:77], s[16:17]
	s_mov_b64 exec, -1
	v_pk_fma_f32 v[232:233], v[106:107], v[78:79], v[114:115]
	v_pk_fma_f32 v[234:235], v[106:107], v[70:71], v[114:115]
	v_pk_fma_f32 v[236:237], v[106:107], v[66:67], v[114:115]
	v_pk_fma_f32 v[238:239], v[106:107], v[74:75], v[114:115]
	v_pk_fma_f32 v[234:235], v[102:103], v[78:79], v[234:235]
	v_pk_fma_f32 v[236:237], v[102:103], v[70:71], v[236:237]
	v_pk_fma_f32 v[238:239], v[102:103], v[66:67], v[238:239]
	v_pk_fma_f32 v[232:233], v[110:111], v[70:71], v[232:233]
; __device__ __forceinline__ unsigned cvt_pk_bf16_asm(float lo, float hi) { unsigned r; asm volatile("v_cvt_pk_bf16_f32 %0, %1, %2" : "=v"(r) : "v"(lo), "v"(hi)); return r; }
;     __device__ __forceinline__ void operator()(const f32x4 (&acc)[2][2][4][2], const Unit& u, int wr, int wc, int fr, int fq) const {
;     ...
;                 for (int bjr = 0; bjr < 2; ++bjr) { const int bj = 1 - bjr; const int co = bj * HALF + 4 * n;
;                     f32x4 U[4];
; #pragma unroll
;                     for (int m = 0; m < 4; ++m) U[m] = acc[ai][bj][m][n] * rs[ai][m] + prm[bj][0];
;                     if (fr < 2) *(f32x4*)(ep + (size_t)fr * NUP + co) = U[0];
;                     if (fr >= 14) *(f32x4*)(ep + (size_t)(fr - 12) * NUP + co) = U[3];
; #pragma unroll
;                     for (int m = 0; m < 4; ++m) { const f32x4 sp = (fr == 15 && m > 0) ? U[m > 0 ? m - 1 : 0] : U[m]; const f32x4 sn = (fr == 0 && m < 3) ? U[m < 3 ? m + 1 : 3] : U[m];
;                         f32x4 pv, nv;
; #pragma unroll
;                         for (int j = 0; j < 4; ++j) { pv[j] = __int_as_float(__builtin_amdgcn_update_dpp(0, __float_as_int(sp[j]), 0x121, 0xf, 0xf, false)); nv[j] = __int_as_float(__builtin_amdgcn_update_dpp(0, __float_as_int(sn[j]), 0x12F, 0xf, 0xf, false)); }
;                         const f32x4 R = prm[bj][1] * pv + prm[bj][2] * U[m] + prm[bj][3] * nv + prm[bj][4];
;                         if (bj == 1) {
; #pragma unroll
;                             for (int j = 0; j < 4; ++j) SG[m][j] = R[j] * __builtin_amdgcn_rcpf(1.0f + __expf(-R[j])); }
;                         else { const int r = row0 + ai * HALF + m * 16; const bool skip = (m == 0 && fr == 0) || (m == 3 && fr == 15);
;                             const f32x4 o = R * SG[m]; u32x2 w; w.x = cvt_pk_bf16_asm(o[0], o[1]); w.y = cvt_pk_bf16_asm(o[2], o[3]);
;                             if (!skip) *(u32x2*)(act + (size_t)r * FFD + u.pn * 128 + wc * 32 + 8 * fq + 4 * n) = w; } } } }
	v_pk_fma_f32 v[234:235], v[110:111], v[66:67], v[234:235]
	v_pk_fma_f32 v[236:237], v[110:111], v[74:75], v[236:237]
	v_fmac_f32_dpp v232, v74, v102 row_ror:1 row_mask:0xf bank_mask:0xf
	v_fmac_f32_dpp v233, v75, v103 row_ror:1 row_mask:0xf bank_mask:0xf
	v_fmac_f32_dpp v238, v78, v110 row_ror:15 row_mask:0xf bank_mask:0xf
	v_fmac_f32_dpp v239, v79, v111 row_ror:15 row_mask:0xf bank_mask:0xf
	v_pk_mul_f32 v[232:233], v[232:233], v[94:95]
	v_pk_mul_f32 v[234:235], v[234:235], v[86:87]
	v_pk_mul_f32 v[236:237], v[236:237], v[82:83]
	v_pk_mul_f32 v[238:239], v[238:239], v[90:91]
	v_cvt_pk_bf16_f32 v78, v232, v233
	v_cvt_pk_bf16_f32 v70, v234, v235
	v_cvt_pk_bf16_f32 v66, v236, v237
	v_cvt_pk_bf16_f32 v74, v238, v239
	v_pk_fma_f32 v[232:233], v[108:109], v[80:81], v[116:117]
	v_pk_fma_f32 v[234:235], v[108:109], v[72:73], v[116:117]
	v_pk_fma_f32 v[236:237], v[108:109], v[68:69], v[116:117]
	v_pk_fma_f32 v[238:239], v[108:109], v[76:77], v[116:117]
	v_pk_fma_f32 v[234:235], v[104:105], v[80:81], v[234:235]
	v_pk_fma_f32 v[236:237], v[104:105], v[72:73], v[236:237]
	v_pk_fma_f32 v[238:239], v[104:105], v[68:69], v[238:239]
	v_pk_fma_f32 v[232:233], v[112:113], v[72:73], v[232:233]
	v_pk_fma_f32 v[234:235], v[112:113], v[68:69], v[234:235]
	v_pk_fma_f32 v[236:237], v[112:113], v[76:77], v[236:237]
	v_fmac_f32_dpp v232, v76, v104 row_ror:1 row_mask:0xf bank_mask:0xf
	v_fmac_f32_dpp v233, v77, v105 row_ror:1 row_mask:0xf bank_mask:0xf
	v_fmac_f32_dpp v238, v80, v112 row_ror:15 row_mask:0xf bank_mask:0xf
	v_fmac_f32_dpp v239, v81, v113 row_ror:15 row_mask:0xf bank_mask:0xf
	v_pk_mul_f32 v[232:233], v[232:233], v[96:97]
	v_pk_mul_f32 v[234:235], v[234:235], v[88:89]
	v_pk_mul_f32 v[236:237], v[236:237], v[84:85]
	v_pk_mul_f32 v[238:239], v[238:239], v[92:93]
	v_cvt_pk_bf16_f32 v79, v232, v233
	v_cvt_pk_bf16_f32 v71, v234, v235
	v_cvt_pk_bf16_f32 v67, v236, v237
	v_cvt_pk_bf16_f32 v75, v238, v239
	s_waitcnt vmcnt(16)
	s_sub_u32 s54, s54, 0x2c000
	s_subb_u32 s55, s55, 0
	v_pk_fma_f32 v[62:63], v[62:63], v[224:225], v[204:205] op_sel_hi:[1,0,1]
	v_pk_fma_f32 v[64:65], v[64:65], v[224:225], v[206:207] op_sel_hi:[1,0,1]
	v_pk_fma_f32 v[54:55], v[54:55], v[224:225], v[204:205] op_sel:[0,1,0] op_sel_hi:[1,1,1]
	v_pk_fma_f32 v[56:57], v[56:57], v[224:225], v[206:207] op_sel:[0,1,0] op_sel_hi:[1,1,1]
	v_pk_fma_f32 v[50:51], v[50:51], v[226:227], v[204:205] op_sel_hi:[1,0,1]
	v_pk_fma_f32 v[52:53], v[52:53], v[226:227], v[206:207] op_sel_hi:[1,0,1]
	v_pk_fma_f32 v[58:59], v[58:59], v[226:227], v[204:205] op_sel:[0,1,0] op_sel_hi:[1,1,1]
	v_pk_fma_f32 v[60:61], v[60:61], v[226:227], v[206:207] op_sel:[0,1,0] op_sel_hi:[1,1,1]
	s_mov_b64 exec, s[4:5]
	global_store_dwordx4 v244, v[62:65], s[54:55] offset:528
	s_add_u32 s16, s54, 0x5800
	s_addc_u32 s17, s55, 0
	global_store_dwordx4 v244, v[54:57], s[16:17] offset:528
	s_mov_b64 exec, s[6:7]
	s_add_u32 s56, s54, 0xb000
	s_addc_u32 s57, s55, 0
	global_store_dwordx4 v244, v[50:53], s[56:57] offset:528
	s_add_u32 s16, s54, 0x10800
	s_addc_u32 s17, s55, 0
	global_store_dwordx4 v244, v[58:61], s[16:17] offset:528
	s_mov_b64 exec, -1
	v_pk_fma_f32 v[232:233], v[212:213], v[62:63], v[220:221]
	v_pk_fma_f32 v[234:235], v[212:213], v[54:55], v[220:221]
	v_pk_fma_f32 v[236:237], v[212:213], v[50:51], v[220:221]
	v_pk_fma_f32 v[238:239], v[212:213], v[58:59], v[220:221]
	v_pk_fma_f32 v[234:235], v[208:209], v[62:63], v[234:235]
	v_pk_fma_f32 v[236:237], v[208:209], v[54:55], v[236:237]
	v_pk_fma_f32 v[238:239], v[208:209], v[50:51], v[238:239]
	v_pk_fma_f32 v[232:233], v[216:217], v[54:55], v[232:233]
	v_pk_fma_f32 v[234:235], v[216:217], v[50:51], v[234:235]
	v_pk_fma_f32 v[236:237], v[216:217], v[58:59], v[236:237]
	v_fmac_f32_dpp v232, v58, v208 row_ror:1 row_mask:0xf bank_mask:0xf
	v_fmac_f32_dpp v233, v59, v209 row_ror:1 row_mask:0xf bank_mask:0xf
	v_fmac_f32_dpp v238, v62, v216 row_ror:15 row_mask:0xf bank_mask:0xf
	v_fmac_f32_dpp v239, v63, v217 row_ror:15 row_mask:0xf bank_mask:0xf
	v_pk_mul_f32 v[62:63], v[232:233], v[240:241]
	v_pk_mul_f32 v[54:55], v[234:235], v[240:241]
	v_pk_mul_f32 v[50:51], v[236:237], v[240:241]
	v_pk_mul_f32 v[58:59], v[238:239], v[240:241]
	v_exp_f32_e32 v62, v62
	v_exp_f32_e32 v63, v63
	v_exp_f32_e32 v54, v54
	v_exp_f32_e32 v55, v55
	v_exp_f32_e32 v50, v50
	v_exp_f32_e32 v51, v51
	v_exp_f32_e32 v58, v58
	v_exp_f32_e32 v59, v59
	v_pk_add_f32 v[62:63], v[62:63], 1.0 op_sel_hi:[1,0]
	v_pk_add_f32 v[54:55], v[54:55], 1.0 op_sel_hi:[1,0]
	v_pk_add_f32 v[50:51], v[50:51], 1.0 op_sel_hi:[1,0]
	v_pk_add_f32 v[58:59], v[58:59], 1.0 op_sel_hi:[1,0]
	v_rcp_f32_e32 v62, v62
	v_rcp_f32_e32 v63, v63
	v_rcp_f32_e32 v54, v54
	v_rcp_f32_e32 v55, v55
	v_rcp_f32_e32 v50, v50
	v_rcp_f32_e32 v51, v51
	v_rcp_f32_e32 v58, v58
	v_rcp_f32_e32 v59, v59
	v_pk_mul_f32 v[62:63], v[232:233], v[62:63]
	v_pk_mul_f32 v[54:55], v[234:235], v[54:55]
	v_pk_mul_f32 v[50:51], v[236:237], v[50:51]
	v_pk_mul_f32 v[58:59], v[238:239], v[58:59]
	v_pk_fma_f32 v[232:233], v[214:215], v[64:65], v[222:223]
	v_pk_fma_f32 v[234:235], v[214:215], v[56:57], v[222:223]
	v_pk_fma_f32 v[236:237], v[214:215], v[52:53], v[222:223]
	v_pk_fma_f32 v[238:239], v[214:215], v[60:61], v[222:223]
	v_pk_fma_f32 v[234:235], v[210:211], v[64:65], v[234:235]
	v_pk_fma_f32 v[236:237], v[210:211], v[56:57], v[236:237]
	v_pk_fma_f32 v[238:239], v[210:211], v[52:53], v[238:239]
	v_pk_fma_f32 v[232:233], v[218:219], v[56:57], v[232:233]
	v_pk_fma_f32 v[234:235], v[218:219], v[52:53], v[234:235]
	v_pk_fma_f32 v[236:237], v[218:219], v[60:61], v[236:237]
	v_fmac_f32_dpp v232, v60, v210 row_ror:1 row_mask:0xf bank_mask:0xf
; __device__ __forceinline__ unsigned cvt_pk_bf16_asm(float lo, float hi) { unsigned r; asm volatile("v_cvt_pk_bf16_f32 %0, %1, %2" : "=v"(r) : "v"(lo), "v"(hi)); return r; }
;     __device__ __forceinline__ void operator()(const f32x4 (&acc)[2][2][4][2], const Unit& u, int wr, int wc, int fr, int fq) const {
;     ...
;                 for (int bjr = 0; bjr < 2; ++bjr) { const int bj = 1 - bjr; const int co = bj * HALF + 4 * n;
;                     f32x4 U[4];
; #pragma unroll
;                     for (int m = 0; m < 4; ++m) U[m] = acc[ai][bj][m][n] * rs[ai][m] + prm[bj][0];
;                     if (fr < 2) *(f32x4*)(ep + (size_t)fr * NUP + co) = U[0];
;                     if (fr >= 14) *(f32x4*)(ep + (size_t)(fr - 12) * NUP + co) = U[3];
; #pragma unroll
;                     for (int m = 0; m < 4; ++m) { const f32x4 sp = (fr == 15 && m > 0) ? U[m > 0 ? m - 1 : 0] : U[m]; const f32x4 sn = (fr == 0 && m < 3) ? U[m < 3 ? m + 1 : 3] : U[m];
;                         f32x4 pv, nv;
; #pragma unroll
;                         for (int j = 0; j < 4; ++j) { pv[j] = __int_as_float(__builtin_amdgcn_update_dpp(0, __float_as_int(sp[j]), 0x121, 0xf, 0xf, false)); nv[j] = __int_as_float(__builtin_amdgcn_update_dpp(0, __float_as_int(sn[j]), 0x12F, 0xf, 0xf, false)); }
;                         const f32x4 R = prm[bj][1] * pv + prm[bj][2] * U[m] + prm[bj][3] * nv + prm[bj][4];
;                         if (bj == 1) {
; #pragma unroll
;                             for (int j = 0; j < 4; ++j) SG[m][j] = R[j] * __builtin_amdgcn_rcpf(1.0f + __expf(-R[j])); }
;                         else { const int r = row0 + ai * HALF + m * 16; const bool skip = (m == 0 && fr == 0) || (m == 3 && fr == 15);
;                             const f32x4 o = R * SG[m]; u32x2 w; w.x = cvt_pk_bf16_asm(o[0], o[1]); w.y = cvt_pk_bf16_asm(o[2], o[3]);
;                             if (!skip) *(u32x2*)(act + (size_t)r * FFD + u.pn * 128 + wc * 32 + 8 * fq + 4 * n) = w; } } } }
	v_fmac_f32_dpp v233, v61, v211 row_ror:1 row_mask:0xf bank_mask:0xf
	v_fmac_f32_dpp v238, v64, v218 row_ror:15 row_mask:0xf bank_mask:0xf
	v_fmac_f32_dpp v239, v65, v219 row_ror:15 row_mask:0xf bank_mask:0xf
	v_pk_mul_f32 v[64:65], v[232:233], v[240:241]
	v_pk_mul_f32 v[56:57], v[234:235], v[240:241]
	v_pk_mul_f32 v[52:53], v[236:237], v[240:241]
	v_pk_mul_f32 v[60:61], v[238:239], v[240:241]
	v_exp_f32_e32 v64, v64
	v_exp_f32_e32 v65, v65
	v_exp_f32_e32 v56, v56
	v_exp_f32_e32 v57, v57
	v_exp_f32_e32 v52, v52
	v_exp_f32_e32 v53, v53
	v_exp_f32_e32 v60, v60
	v_exp_f32_e32 v61, v61
	v_pk_add_f32 v[64:65], v[64:65], 1.0 op_sel_hi:[1,0]
	v_pk_add_f32 v[56:57], v[56:57], 1.0 op_sel_hi:[1,0]
	v_pk_add_f32 v[52:53], v[52:53], 1.0 op_sel_hi:[1,0]
	v_pk_add_f32 v[60:61], v[60:61], 1.0 op_sel_hi:[1,0]
	v_rcp_f32_e32 v64, v64
	v_rcp_f32_e32 v65, v65
	v_rcp_f32_e32 v56, v56
	v_rcp_f32_e32 v57, v57
	v_rcp_f32_e32 v52, v52
	v_rcp_f32_e32 v53, v53
	v_rcp_f32_e32 v60, v60
	v_rcp_f32_e32 v61, v61
	v_pk_mul_f32 v[64:65], v[232:233], v[64:65]
	v_pk_mul_f32 v[56:57], v[234:235], v[56:57]
	v_pk_mul_f32 v[52:53], v[236:237], v[52:53]
	v_pk_mul_f32 v[60:61], v[238:239], v[60:61]
	v_pk_fma_f32 v[46:47], v[46:47], v[224:225], v[184:185] op_sel_hi:[1,0,1]
	v_pk_fma_f32 v[48:49], v[48:49], v[224:225], v[186:187] op_sel_hi:[1,0,1]
	v_pk_fma_f32 v[38:39], v[38:39], v[224:225], v[184:185] op_sel:[0,1,0] op_sel_hi:[1,1,1]
	v_pk_fma_f32 v[40:41], v[40:41], v[224:225], v[186:187] op_sel:[0,1,0] op_sel_hi:[1,1,1]
	v_pk_fma_f32 v[34:35], v[34:35], v[226:227], v[184:185] op_sel_hi:[1,0,1]
	v_pk_fma_f32 v[36:37], v[36:37], v[226:227], v[186:187] op_sel_hi:[1,0,1]
	v_pk_fma_f32 v[42:43], v[42:43], v[226:227], v[184:185] op_sel:[0,1,0] op_sel_hi:[1,1,1]
	v_pk_fma_f32 v[44:45], v[44:45], v[226:227], v[186:187] op_sel:[0,1,0] op_sel_hi:[1,1,1]
	s_mov_b64 exec, s[4:5]
	global_store_dwordx4 v244, v[46:49], s[54:55] offset:16
	s_add_u32 s16, s54, 0x5800
	s_addc_u32 s17, s55, 0
	global_store_dwordx4 v244, v[38:41], s[16:17] offset:16
	s_mov_b64 exec, s[6:7]
	s_add_u32 s56, s54, 0xb000
	s_addc_u32 s57, s55, 0
	global_store_dwordx4 v244, v[34:37], s[56:57] offset:16
	s_add_u32 s16, s54, 0x10800
	s_addc_u32 s17, s55, 0
	global_store_dwordx4 v244, v[42:45], s[16:17] offset:16
	s_mov_b64 exec, -1
	v_pk_fma_f32 v[232:233], v[192:193], v[46:47], v[200:201]
	v_pk_fma_f32 v[234:235], v[192:193], v[38:39], v[200:201]
	v_pk_fma_f32 v[236:237], v[192:193], v[34:35], v[200:201]
	v_pk_fma_f32 v[238:239], v[192:193], v[42:43], v[200:201]
	v_pk_fma_f32 v[234:235], v[188:189], v[46:47], v[234:235]
	v_pk_fma_f32 v[236:237], v[188:189], v[38:39], v[236:237]
	v_pk_fma_f32 v[238:239], v[188:189], v[34:35], v[238:239]
	v_pk_fma_f32 v[232:233], v[196:197], v[38:39], v[232:233]
	v_pk_fma_f32 v[234:235], v[196:197], v[34:35], v[234:235]
	v_pk_fma_f32 v[236:237], v[196:197], v[42:43], v[236:237]
	v_fmac_f32_dpp v232, v42, v188 row_ror:1 row_mask:0xf bank_mask:0xf
	v_fmac_f32_dpp v233, v43, v189 row_ror:1 row_mask:0xf bank_mask:0xf
	v_fmac_f32_dpp v238, v46, v196 row_ror:15 row_mask:0xf bank_mask:0xf
	v_fmac_f32_dpp v239, v47, v197 row_ror:15 row_mask:0xf bank_mask:0xf
	v_pk_mul_f32 v[232:233], v[232:233], v[62:63]
	v_pk_mul_f32 v[234:235], v[234:235], v[54:55]
	v_pk_mul_f32 v[236:237], v[236:237], v[50:51]
	v_pk_mul_f32 v[238:239], v[238:239], v[58:59]
	v_cvt_pk_bf16_f32 v148, v232, v233
	v_cvt_pk_bf16_f32 v136, v234, v235
	v_cvt_pk_bf16_f32 v132, v236, v237
	v_cvt_pk_bf16_f32 v144, v238, v239
	v_pk_fma_f32 v[232:233], v[194:195], v[48:49], v[202:203]
	v_pk_fma_f32 v[234:235], v[194:195], v[40:41], v[202:203]
	v_pk_fma_f32 v[236:237], v[194:195], v[36:37], v[202:203]
	v_pk_fma_f32 v[238:239], v[194:195], v[44:45], v[202:203]
	v_pk_fma_f32 v[234:235], v[190:191], v[48:49], v[234:235]
	v_pk_fma_f32 v[236:237], v[190:191], v[40:41], v[236:237]
	v_pk_fma_f32 v[238:239], v[190:191], v[36:37], v[238:239]
	v_pk_fma_f32 v[232:233], v[198:199], v[40:41], v[232:233]
	v_pk_fma_f32 v[234:235], v[198:199], v[36:37], v[234:235]
	v_pk_fma_f32 v[236:237], v[198:199], v[44:45], v[236:237]
	v_fmac_f32_dpp v232, v44, v190 row_ror:1 row_mask:0xf bank_mask:0xf
	v_fmac_f32_dpp v233, v45, v191 row_ror:1 row_mask:0xf bank_mask:0xf
	v_fmac_f32_dpp v238, v48, v198 row_ror:15 row_mask:0xf bank_mask:0xf
	v_fmac_f32_dpp v239, v49, v199 row_ror:15 row_mask:0xf bank_mask:0xf
	v_pk_mul_f32 v[232:233], v[232:233], v[64:65]
	v_pk_mul_f32 v[234:235], v[234:235], v[56:57]
	v_pk_mul_f32 v[236:237], v[236:237], v[52:53]
	v_pk_mul_f32 v[238:239], v[238:239], v[60:61]
	v_cvt_pk_bf16_f32 v149, v232, v233
	v_cvt_pk_bf16_f32 v137, v234, v235
	v_cvt_pk_bf16_f32 v133, v236, v237
	v_cvt_pk_bf16_f32 v145, v238, v239
	s_add_u32 s16, s74, 0x0
	s_addc_u32 s17, s75, 0
	s_not_b64 exec, s[4:5]
	global_store_dwordx4 v245, v[146:149], s[16:17]
	s_mov_b64 exec, -1
	s_add_u32 s16, s74, 0x1600
	s_addc_u32 s17, s75, 0
	global_store_dwordx4 v245, v[134:137], s[16:17]
	s_add_u32 s16, s74, 0x2c00
	s_addc_u32 s17, s75, 0
	global_store_dwordx4 v245, v[130:133], s[16:17]
	s_add_u32 s16, s74, 0x4200
	s_addc_u32 s17, s75, 0
	s_not_b64 exec, s[6:7]
	global_store_dwordx4 v245, v[142:145], s[16:17]
	s_mov_b64 exec, -1
	s_add_u32 s54, s54, 0x2c000
	s_addc_u32 s55, s55, 0
	v_pk_fma_f32 v[30:31], v[30:31], v[228:229], v[204:205] op_sel_hi:[1,0,1]
	v_pk_fma_f32 v[32:33], v[32:33], v[228:229], v[206:207] op_sel_hi:[1,0,1]
	v_pk_fma_f32 v[26:27], v[26:27], v[228:229], v[204:205] op_sel:[0,1,0] op_sel_hi:[1,1,1]
	v_pk_fma_f32 v[28:29], v[28:29], v[228:229], v[206:207] op_sel:[0,1,0] op_sel_hi:[1,1,1]
	v_pk_fma_f32 v[18:19], v[18:19], v[230:231], v[204:205] op_sel_hi:[1,0,1]
;     __device__ __forceinline__ void operator()(const f32x4 (&acc)[2][2][4][2], const Unit& u, int wr, int wc, int fr, int fq) const {
;     ...
;                 for (int bjr = 0; bjr < 2; ++bjr) { const int bj = 1 - bjr; const int co = bj * HALF + 4 * n;
;                     f32x4 U[4];
; #pragma unroll
;                     for (int m = 0; m < 4; ++m) U[m] = acc[ai][bj][m][n] * rs[ai][m] + prm[bj][0];
;                     if (fr < 2) *(f32x4*)(ep + (size_t)fr * NUP + co) = U[0];
;                     if (fr >= 14) *(f32x4*)(ep + (size_t)(fr - 12) * NUP + co) = U[3];
; #pragma unroll
;                     for (int m = 0; m < 4; ++m) { const f32x4 sp = (fr == 15 && m > 0) ? U[m > 0 ? m - 1 : 0] : U[m]; const f32x4 sn = (fr == 0 && m < 3) ? U[m < 3 ? m + 1 : 3] : U[m];
;                         f32x4 pv, nv;
; #pragma unroll
;                         for (int j = 0; j < 4; ++j) { pv[j] = __int_as_float(__builtin_amdgcn_update_dpp(0, __float_as_int(sp[j]), 0x121, 0xf, 0xf, false)); nv[j] = __int_as_float(__builtin_amdgcn_update_dpp(0, __float_as_int(sn[j]), 0x12F, 0xf, 0xf, false)); }
;                         const f32x4 R = prm[bj][1] * pv + prm[bj][2] * U[m] + prm[bj][3] * nv + prm[bj][4];
;                         if (bj == 1) {
; #pragma unroll
;                             for (int j = 0; j < 4; ++j) SG[m][j] = R[j] * __builtin_amdgcn_rcpf(1.0f + __expf(-R[j])); }
	v_pk_fma_f32 v[20:21], v[20:21], v[230:231], v[206:207] op_sel_hi:[1,0,1]
	v_pk_fma_f32 v[22:23], v[22:23], v[230:231], v[204:205] op_sel:[0,1,0] op_sel_hi:[1,1,1]
	v_pk_fma_f32 v[24:25], v[24:25], v[230:231], v[206:207] op_sel:[0,1,0] op_sel_hi:[1,1,1]
	s_mov_b64 exec, s[4:5]
	global_store_dwordx4 v244, v[30:33], s[54:55] offset:528
	s_add_u32 s16, s54, 0x5800
	s_addc_u32 s17, s55, 0
	global_store_dwordx4 v244, v[26:29], s[16:17] offset:528
	s_mov_b64 exec, s[6:7]
	s_add_u32 s56, s54, 0xb000
	s_addc_u32 s57, s55, 0
	global_store_dwordx4 v244, v[18:21], s[56:57] offset:528
	s_add_u32 s16, s54, 0x10800
	s_addc_u32 s17, s55, 0
	global_store_dwordx4 v244, v[22:25], s[16:17] offset:528
	s_mov_b64 exec, -1
	v_pk_fma_f32 v[232:233], v[212:213], v[30:31], v[220:221]
	v_pk_fma_f32 v[234:235], v[212:213], v[26:27], v[220:221]
	v_pk_fma_f32 v[236:237], v[212:213], v[18:19], v[220:221]
	v_pk_fma_f32 v[238:239], v[212:213], v[22:23], v[220:221]
	v_pk_fma_f32 v[234:235], v[208:209], v[30:31], v[234:235]
	v_pk_fma_f32 v[236:237], v[208:209], v[26:27], v[236:237]
	v_pk_fma_f32 v[238:239], v[208:209], v[18:19], v[238:239]
	v_pk_fma_f32 v[232:233], v[216:217], v[26:27], v[232:233]
	v_pk_fma_f32 v[234:235], v[216:217], v[18:19], v[234:235]
	v_pk_fma_f32 v[236:237], v[216:217], v[22:23], v[236:237]
	v_fmac_f32_dpp v232, v22, v208 row_ror:1 row_mask:0xf bank_mask:0xf
	v_fmac_f32_dpp v233, v23, v209 row_ror:1 row_mask:0xf bank_mask:0xf
	v_fmac_f32_dpp v238, v30, v216 row_ror:15 row_mask:0xf bank_mask:0xf
	v_fmac_f32_dpp v239, v31, v217 row_ror:15 row_mask:0xf bank_mask:0xf
	v_pk_mul_f32 v[30:31], v[232:233], v[240:241]
	v_pk_mul_f32 v[26:27], v[234:235], v[240:241]
	v_pk_mul_f32 v[18:19], v[236:237], v[240:241]
	v_pk_mul_f32 v[22:23], v[238:239], v[240:241]
	v_exp_f32_e32 v30, v30
	v_exp_f32_e32 v31, v31
	v_exp_f32_e32 v26, v26
	v_exp_f32_e32 v27, v27
	v_exp_f32_e32 v18, v18
	v_exp_f32_e32 v19, v19
	v_exp_f32_e32 v22, v22
	v_exp_f32_e32 v23, v23
	v_pk_add_f32 v[30:31], v[30:31], 1.0 op_sel_hi:[1,0]
	v_pk_add_f32 v[26:27], v[26:27], 1.0 op_sel_hi:[1,0]
	v_pk_add_f32 v[18:19], v[18:19], 1.0 op_sel_hi:[1,0]
	v_pk_add_f32 v[22:23], v[22:23], 1.0 op_sel_hi:[1,0]
	v_rcp_f32_e32 v30, v30
	v_rcp_f32_e32 v31, v31
	v_rcp_f32_e32 v26, v26
	v_rcp_f32_e32 v27, v27
	v_rcp_f32_e32 v18, v18
	v_rcp_f32_e32 v19, v19
	v_rcp_f32_e32 v22, v22
	v_rcp_f32_e32 v23, v23
	v_pk_mul_f32 v[30:31], v[232:233], v[30:31]
	v_pk_mul_f32 v[26:27], v[234:235], v[26:27]
	v_pk_mul_f32 v[18:19], v[236:237], v[18:19]
	v_pk_mul_f32 v[22:23], v[238:239], v[22:23]
	v_pk_fma_f32 v[232:233], v[214:215], v[32:33], v[222:223]
	v_pk_fma_f32 v[234:235], v[214:215], v[28:29], v[222:223]
	v_pk_fma_f32 v[236:237], v[214:215], v[20:21], v[222:223]
	v_pk_fma_f32 v[238:239], v[214:215], v[24:25], v[222:223]
	v_pk_fma_f32 v[234:235], v[210:211], v[32:33], v[234:235]
	v_pk_fma_f32 v[236:237], v[210:211], v[28:29], v[236:237]
	v_pk_fma_f32 v[238:239], v[210:211], v[20:21], v[238:239]
	v_pk_fma_f32 v[232:233], v[218:219], v[28:29], v[232:233]
	v_pk_fma_f32 v[234:235], v[218:219], v[20:21], v[234:235]
	v_pk_fma_f32 v[236:237], v[218:219], v[24:25], v[236:237]
	v_fmac_f32_dpp v232, v24, v210 row_ror:1 row_mask:0xf bank_mask:0xf
	v_fmac_f32_dpp v233, v25, v211 row_ror:1 row_mask:0xf bank_mask:0xf
	v_fmac_f32_dpp v238, v32, v218 row_ror:15 row_mask:0xf bank_mask:0xf
	v_fmac_f32_dpp v239, v33, v219 row_ror:15 row_mask:0xf bank_mask:0xf
	v_pk_mul_f32 v[32:33], v[232:233], v[240:241]
	v_pk_mul_f32 v[28:29], v[234:235], v[240:241]
	v_pk_mul_f32 v[20:21], v[236:237], v[240:241]
	v_pk_mul_f32 v[24:25], v[238:239], v[240:241]
	v_exp_f32_e32 v32, v32
	v_exp_f32_e32 v33, v33
	v_exp_f32_e32 v28, v28
	v_exp_f32_e32 v29, v29
	v_exp_f32_e32 v20, v20
	v_exp_f32_e32 v21, v21
	v_exp_f32_e32 v24, v24
	v_exp_f32_e32 v25, v25
	v_pk_add_f32 v[32:33], v[32:33], 1.0 op_sel_hi:[1,0]
	v_pk_add_f32 v[28:29], v[28:29], 1.0 op_sel_hi:[1,0]
	v_pk_add_f32 v[20:21], v[20:21], 1.0 op_sel_hi:[1,0]
	v_pk_add_f32 v[24:25], v[24:25], 1.0 op_sel_hi:[1,0]
	v_rcp_f32_e32 v32, v32
	v_rcp_f32_e32 v33, v33
	v_rcp_f32_e32 v28, v28
	v_rcp_f32_e32 v29, v29
	v_rcp_f32_e32 v20, v20
	v_rcp_f32_e32 v21, v21
	v_rcp_f32_e32 v24, v24
; __device__ __forceinline__ int otid(int wv) { int t; asm volatile("v_mbcnt_lo_u32_b32 %0, -1, 0\n\tv_mbcnt_hi_u32_b32 %0, -1, %0\n\tv_lshl_add_u32 %0, %1, 6, %0" : "=&v"(t) : "s"(wv)); return t; }
; __device__ __forceinline__ unsigned cvt_pk_bf16_asm(float lo, float hi) { unsigned r; asm volatile("v_cvt_pk_bf16_f32 %0, %1, %2" : "=v"(r) : "v"(lo), "v"(hi)); return r; }
; template <class Epi>
; __device__ __forceinline__ void gemm_phase(int wv, LAS unsigned char* lds, const Gemm g, const StaticOrder& S, const Epi& E) {
;     ...
;         { const int t2_ = otid(wv); E(acc, cur, wr, wc, t2_ & 15, (t2_ & 63) >> 4); }
;         if (!has_next) break;
; #pragma unroll
;         for (int a = 0; a < 2; ++a)
; #pragma unroll
;             for (int b = 0; b < 2; ++b)
; #pragma unroll
;                 for (int m = 0; m < 4; ++m)
; #pragma unroll
;                     for (int n = 0; n < 2; ++n) acc[a][b][m][n] = (f32x4){0.f, 0.f, 0.f, 0.f};
;         cur = nxt; cA = nA; cB = nB; ++ui;
;     __device__ __forceinline__ void operator()(const f32x4 (&acc)[2][2][4][2], const Unit& u, int wr, int wc, int fr, int fq) const {
;     ...
;                         else { const int r = row0 + ai * HALF + m * 16; const bool skip = (m == 0 && fr == 0) || (m == 3 && fr == 15);
;                             const f32x4 o = R * SG[m]; u32x2 w; w.x = cvt_pk_bf16_asm(o[0], o[1]); w.y = cvt_pk_bf16_asm(o[2], o[3]);
;                             if (!skip) *(u32x2*)(act + (size_t)r * FFD + u.pn * 128 + wc * 32 + 8 * fq + 4 * n) = w; } } } }
	v_rcp_f32_e32 v25, v25
	v_pk_mul_f32 v[32:33], v[232:233], v[32:33]
	v_pk_mul_f32 v[28:29], v[234:235], v[28:29]
	v_pk_mul_f32 v[20:21], v[236:237], v[20:21]
	v_pk_mul_f32 v[24:25], v[238:239], v[24:25]
	v_pk_fma_f32 v[14:15], v[14:15], v[228:229], v[184:185] op_sel_hi:[1,0,1]
	v_pk_fma_f32 v[16:17], v[16:17], v[228:229], v[186:187] op_sel_hi:[1,0,1]
	v_pk_fma_f32 v[6:7], v[6:7], v[228:229], v[184:185] op_sel:[0,1,0] op_sel_hi:[1,1,1]
	v_pk_fma_f32 v[8:9], v[8:9], v[228:229], v[186:187] op_sel:[0,1,0] op_sel_hi:[1,1,1]
	v_pk_fma_f32 v[2:3], v[2:3], v[230:231], v[184:185] op_sel_hi:[1,0,1]
	v_pk_fma_f32 v[4:5], v[4:5], v[230:231], v[186:187] op_sel_hi:[1,0,1]
	v_pk_fma_f32 v[10:11], v[10:11], v[230:231], v[184:185] op_sel:[0,1,0] op_sel_hi:[1,1,1]
	v_pk_fma_f32 v[12:13], v[12:13], v[230:231], v[186:187] op_sel:[0,1,0] op_sel_hi:[1,1,1]
	s_mov_b64 exec, s[4:5]
	global_store_dwordx4 v244, v[14:17], s[54:55] offset:16
	s_add_u32 s16, s54, 0x5800
	s_addc_u32 s17, s55, 0
	global_store_dwordx4 v244, v[6:9], s[16:17] offset:16
	s_mov_b64 exec, s[6:7]
	s_add_u32 s56, s54, 0xb000
	s_addc_u32 s57, s55, 0
	global_store_dwordx4 v244, v[2:5], s[56:57] offset:16
	s_add_u32 s16, s54, 0x10800
	s_addc_u32 s17, s55, 0
	global_store_dwordx4 v244, v[10:13], s[16:17] offset:16
	s_mov_b64 exec, -1
	v_pk_fma_f32 v[232:233], v[192:193], v[14:15], v[200:201]
	v_pk_fma_f32 v[234:235], v[192:193], v[6:7], v[200:201]
	v_pk_fma_f32 v[236:237], v[192:193], v[2:3], v[200:201]
	v_pk_fma_f32 v[238:239], v[192:193], v[10:11], v[200:201]
	v_pk_fma_f32 v[234:235], v[188:189], v[14:15], v[234:235]
	v_pk_fma_f32 v[236:237], v[188:189], v[6:7], v[236:237]
	v_pk_fma_f32 v[238:239], v[188:189], v[2:3], v[238:239]
	v_pk_fma_f32 v[232:233], v[196:197], v[6:7], v[232:233]
	v_pk_fma_f32 v[234:235], v[196:197], v[2:3], v[234:235]
	v_pk_fma_f32 v[236:237], v[196:197], v[10:11], v[236:237]
	v_fmac_f32_dpp v232, v10, v188 row_ror:1 row_mask:0xf bank_mask:0xf
	v_fmac_f32_dpp v233, v11, v189 row_ror:1 row_mask:0xf bank_mask:0xf
	v_fmac_f32_dpp v238, v14, v196 row_ror:15 row_mask:0xf bank_mask:0xf
	v_fmac_f32_dpp v239, v15, v197 row_ror:15 row_mask:0xf bank_mask:0xf
	v_pk_mul_f32 v[232:233], v[232:233], v[30:31]
	v_pk_mul_f32 v[234:235], v[234:235], v[26:27]
	v_pk_mul_f32 v[236:237], v[236:237], v[18:19]
	v_pk_mul_f32 v[238:239], v[238:239], v[22:23]
	v_cvt_pk_bf16_f32 v80, v232, v233
	v_cvt_pk_bf16_f32 v72, v234, v235
	v_cvt_pk_bf16_f32 v68, v236, v237
	v_cvt_pk_bf16_f32 v76, v238, v239
	v_pk_fma_f32 v[232:233], v[194:195], v[16:17], v[202:203]
	v_pk_fma_f32 v[234:235], v[194:195], v[8:9], v[202:203]
	v_pk_fma_f32 v[236:237], v[194:195], v[4:5], v[202:203]
	v_pk_fma_f32 v[238:239], v[194:195], v[12:13], v[202:203]
	v_pk_fma_f32 v[234:235], v[190:191], v[16:17], v[234:235]
	v_pk_fma_f32 v[236:237], v[190:191], v[8:9], v[236:237]
	v_pk_fma_f32 v[238:239], v[190:191], v[4:5], v[238:239]
	v_pk_fma_f32 v[232:233], v[198:199], v[8:9], v[232:233]
	v_pk_fma_f32 v[234:235], v[198:199], v[4:5], v[234:235]
	v_pk_fma_f32 v[236:237], v[198:199], v[12:13], v[236:237]
	v_fmac_f32_dpp v232, v12, v190 row_ror:1 row_mask:0xf bank_mask:0xf
	v_fmac_f32_dpp v233, v13, v191 row_ror:1 row_mask:0xf bank_mask:0xf
	v_fmac_f32_dpp v238, v16, v198 row_ror:15 row_mask:0xf bank_mask:0xf
	v_fmac_f32_dpp v239, v17, v199 row_ror:15 row_mask:0xf bank_mask:0xf
	v_pk_mul_f32 v[232:233], v[232:233], v[32:33]
	v_pk_mul_f32 v[234:235], v[234:235], v[28:29]
	v_pk_mul_f32 v[236:237], v[236:237], v[20:21]
	v_pk_mul_f32 v[238:239], v[238:239], v[24:25]
	v_cvt_pk_bf16_f32 v81, v232, v233
	v_cvt_pk_bf16_f32 v73, v234, v235
	v_cvt_pk_bf16_f32 v69, v236, v237
	v_cvt_pk_bf16_f32 v77, v238, v239
	s_add_u32 s16, s74, 0xb0000
	s_addc_u32 s17, s75, 0
	s_not_b64 exec, s[4:5]
	global_store_dwordx4 v245, v[78:81], s[16:17]
	s_mov_b64 exec, -1
	s_add_u32 s16, s74, 0xb1600
	s_addc_u32 s17, s75, 0
	global_store_dwordx4 v245, v[70:73], s[16:17]
	s_add_u32 s16, s74, 0xb2c00
	s_addc_u32 s17, s75, 0
	global_store_dwordx4 v245, v[66:69], s[16:17]
	s_add_u32 s16, s74, 0xb4200
	s_addc_u32 s17, s75, 0
	s_not_b64 exec, s[6:7]
	global_store_dwordx4 v245, v[74:77], s[16:17]
	s_mov_b64 exec, -1
	s_branch .LBB0_451
